# weight conversion of later layers moved into idle windows (in-proj tail, scan shadow, gate-up tail; static assignment) + scan inversion on VALU + residual-epilogue load prefetch
# speedup vs baseline: 1.0092x; 1.0092x over previous
;     __device__ __forceinline__ const float* in(int i) const { return (const float*)(const GAS float*)raw(i); }
;     __device__ __forceinline__ unsigned char* ws() const { return (unsigned char*)(GAS unsigned char*)raw(N_INPUTS + 1); }
; __device__ __forceinline__ CvItem cv_decode(const PT& a, int l, int r) {
;     unsigned char* ws = a.ws(); CvItem it;
;     if (r < IT_WIN) { const int kb = r / 458, nb = r % 458, n0 = nb * 32;
;         int drow; if (n0 < 2048) drow = n0; else if (n0 < 5120) drow = NIN_MAIN + (n0 - 2048); else if (n0 < 8512) drow = 2048 + (n0 - 5120); else drow = 5632 + (n0 - 8512);
;         it = CvItem{a.in(I_W_IN) + (size_t)l * D * NIN, NIN, kb * 64, n0, (bf16_t*)(ws + WS_WIN + l * WIN_L), D, drow, a.in(I_NORM_MIX_G) + l * D}; return it; }
;     r -= IT_WIN;
;     if (r < 3 * IT_BR) { const int br = r / IT_BR; r -= br * IT_BR; const int kb = r / 64, nb = r % 64;
;         it = CvItem{a.in(br == 0 ? I_W_BR_A : (br == 1 ? I_W_BR_B : I_W_BR_C)) + (size_t)l * 1024 * D, D, kb * 64, nb * 32, (bf16_t*)(ws + WS_WBR + l * WBR_L) + (size_t)br * D * 1024, 1024, nb * 32, nullptr}; return it; }
;     r -= 3 * IT_BR;
;     if (r < IT_OUT) { const int kb = r / 64, nb = r % 64;
;         it = CvItem{a.in(I_W_OUT) + (size_t)l * D * D, D, kb * 64, nb * 32, (bf16_t*)(ws + WS_WOUT + l * WOUT_L), D, nb * 32, nullptr}; return it; }
;     r -= IT_OUT;
;     if (r < 2 * IT_GU) { const int up = r / IT_GU; r -= up * IT_GU; const int kb = r / 176, nb = r % 176, n0 = nb * 32;
;         it = CvItem{a.in(up ? I_W_FFN_UP : I_W_FFN_GATE) + (size_t)l * D * DFF, DFF, kb * 64, n0, (bf16_t*)(ws + WS_WGU + l * WGU_L), D, 256 * (n0 / 128) + (n0 % 128) + 128 * up, a.in(I_NORM_FFN_G) + l * D}; return it; }
;     r -= 2 * IT_GU;
;     { const int kb = r / 64, nb = r % 64;
;       it = CvItem{a.in(I_W_FFN_DOWN) + (size_t)l * DFF * D, D, kb * 64, nb * 32, (bf16_t*)(ws + WS_WDN + l * WDN_L), DFF, nb * 32, nullptr}; }
;     return it;
; }
; __device__ __forceinline__ void prologue_a(const PT& a, LAS unsigned char* lds) {
;     ...
;     convert_layer_static(a, lds, 0, gw, NGW, wave, lane);
;     for (int cl_ = 1; cl_ < DEPTH; ++cl_) convert_layer_static(a, lds, cl_, gw, NGW, wave, lane, CV_PRO_ITEMS);
.LBB0_110:
	s_or_b64 exec, exec, s[12:13]
	v_lshl_add_u32 v2, v74, 2, v115
	v_add_u32_e32 v3, v115, v113
	s_mov_b32 s13, 0
	v_lshl_add_u32 v113, v67, 2, v3
	v_lshl_add_u32 v115, v69, 2, v3
	v_lshl_add_u32 v117, v97, 2, v3
	v_lshl_add_u32 v119, v99, 2, v3
	s_mov_b32 s18, 1
	s_lshl_b32 s42, s17, 5
	s_movk_i32 s43, 0x393f
	s_movk_i32 s44, 0x453f
	s_movk_i32 s45, 0x4d3f
	s_movk_i32 s46, 0x793f
	s_movk_i32 s47, 0x15ff
	s_movk_i32 s48, 0xba3
	s_movk_i32 s49, 0x1600
	s_movk_i32 s50, 0x3ff
	v_mov_b32_e32 v79, 0
	s_mov_b64 s[20:21], 0xea00000
	s_mov_b32 s51, 0x478bbced
	s_movk_i32 s52, 0x9f
	s_movk_i32 s53, 0x109
	v_add_u32_e32 v121, v2, v121
	v_lshlrev_b64 v[76:77], 1, v[76:77]
	s_mov_b32 s54, 0x673f
	v_mov_b32_e32 v123, 0xea00
	v_mov_b32_e32 v125, 5
	v_mov_b32_e32 v128, 0x23a40
	v_mov_b32_e32 v129, 0x23a38
	v_mov_b32_e32 v130, 6
	v_mov_b32_e32 v131, 0x80
	v_mov_b32_e32 v132, 0x23a20
	v_mov_b32_e32 v133, 0x23a18
	v_mov_b32_e32 v134, 0x23a10
	s_branch .LBB0_112

;     __device__ __forceinline__ const float* in(int i) const { return (const float*)(const GAS float*)raw(i); }
;     __device__ __forceinline__ unsigned char* ws() const { return (unsigned char*)(GAS unsigned char*)raw(N_INPUTS + 1); }
; __device__ __forceinline__ CvItem cv_decode(const PT& a, int l, int r) {
;     unsigned char* ws = a.ws(); CvItem it;
;     if (r < IT_WIN) { const int kb = r / 458, nb = r % 458, n0 = nb * 32;
;         int drow; if (n0 < 2048) drow = n0; else if (n0 < 5120) drow = NIN_MAIN + (n0 - 2048); else if (n0 < 8512) drow = 2048 + (n0 - 5120); else drow = 5632 + (n0 - 8512);
;         it = CvItem{a.in(I_W_IN) + (size_t)l * D * NIN, NIN, kb * 64, n0, (bf16_t*)(ws + WS_WIN + l * WIN_L), D, drow, a.in(I_NORM_MIX_G) + l * D}; return it; }
;     for (int it = 0; it < budget; ++it) {
;         unsigned r = 0; if (lane == 0) r = __hip_atomic_fetch_add(ctr, 2u, __ATOMIC_RELAXED, __HIP_MEMORY_SCOPE_AGENT);
;         r = (unsigned)__builtin_amdgcn_readfirstlane((int)r) + (unsigned)CV_PRO_ITEMS;
;         if (r >= (unsigned)IT_LAYER) break;
;         cv_pair(a, lds, l, (int)r, wave, lane);
;     }
; }
.LcvqA_1381:
	s_mov_b32 s24, s100
	s_add_u32 s100, s100, 0xc00
	s_add_i32 s24, s24, 0xffffd800
	s_cmp_lt_u32 s24, 0xffff70c0
	s_mov_b64 s[2:3], -1
	s_cbranch_scc1 .LcvqA_1380
	v_mov_b32_e32 v2, 0x23a60
	s_add_i32 s15, s24, 0x8f40
	v_add_u32_e32 v2, 0, v2
	ds_read_b64 v[2:3], v2
	s_cmpk_gt_u32 s15, 0x393f
	s_waitcnt lgkmcnt(0)
	v_readfirstlane_b32 s20, v3
	v_readfirstlane_b32 s21, v2
	s_cbranch_scc0 .LcvqA_1399
	s_cmpk_gt_u32 s15, 0x453f
	s_cbranch_scc0 .LcvqA_1396
	s_cmpk_gt_u32 s15, 0x4d3f
	s_mov_b64 s[18:19], -1
	s_cbranch_scc0 .LcvqA_1393
	s_cmpk_gt_u32 s15, 0x793f
	s_cbranch_scc0 .LcvqA_1391
	v_mov_b32_e32 v2, 0x23a48
	s_and_b32 s2, s15, 0x7fffffc0
	v_add_u32_e32 v2, 0, v2
	ds_read_b64 v[2:3], v2
	s_add_i32 s14, s2, 0xffff86c0
	s_waitcnt lgkmcnt(0)
	v_readfirstlane_b32 s3, v2
	v_readfirstlane_b32 s2, v3
	s_add_u32 s30, s3, s34
	s_addc_u32 s31, s2, s33
	s_lshl_b32 s2, s15, 5
	s_and_b32 s25, s2, 0x7e0
	s_add_u32 s2, s21, s50
	s_addc_u32 s3, s20, s35
	s_add_u32 s12, s2, 0x1ea00000
	s_addc_u32 s13, s3, 0
	s_mov_b64 s[2:3], 0

; #define LAS __attribute__((address_space(3)))
; __device__ __forceinline__ int opaque_tid() { int t = threadIdx.x; asm volatile("" : "+v"(t)); return t; }
; __device__ __forceinline__ void cv_pair(const PT& a, LAS unsigned char* lds, int l, int r, int wave, int lane) {
;     LAS float* s0 = (LAS float*)(lds + wave * CV_WAVE_B); LAS float* s1 = (LAS float*)(lds + wave * CV_WAVE_B + CV_TILE_B);
;     const bool two = r + 1 < IT_LAYER;
;     const CvItem i0 = cv_decode(a, l, r), i1 = cv_decode(a, l, two ? r + 1 : r);
;     f32x4 v0[8], v1[8]; float g0[8], g1[8];
;     cv_load(i0, lane, v0, g0); cv_load(i1, lane, v1, g1);
;     cv_lds_write(s0, lane, v0, g0); cv_lds_write(s1, lane, v1, g1);
;     asm volatile("s_waitcnt lgkmcnt(0)" ::: "memory");
;     cv_store(i0, s0, lane); if (two) cv_store(i1, s1, lane);
;     asm volatile("s_waitcnt lgkmcnt(0)" ::: "memory");
; }
; __global__ void __launch_bounds__(NTHREADS, 2) mk_fwd(Args args) {
;     ...
;             if (l + 1 < DEPTH && !(G >= 256 && bid < 128)) { __syncthreads(); const int tid_ = opaque_tid(); convert_layer_queue(pt, lds, l + 1, cvq, tid_ >> 6, tid_ & 63); }
.LBB0_1377:
	s_cmp_eq_u32 s64, 3
	v_readlane_b32 s2, v253, 61
	s_cselect_b64 s[0:1], -1, 0
	v_readlane_b32 s3, v253, 62
	s_or_b64 s[0:1], s[2:3], s[0:1]
	v_readlane_b32 s28, v254, 55
	s_mov_b32 s36, s64
	s_and_b64 vcc, exec, s[0:1]
	v_readlane_b32 s29, v254, 56
	s_cbranch_vccnz .LBB0_1470
	v_readlane_b32 s0, v254, 53
	v_readlane_b32 s1, v254, 54
	s_mov_b32 s3, s1
	s_lshl_b32 s2, s36, 6
	s_lshl_b64 s[0:1], s[2:3], 2
	v_readlane_b32 s4, v254, 60
	v_readlane_b32 s5, v254, 61
	s_add_u32 s0, s4, s0
	s_addc_u32 s1, s5, s1
	s_add_u32 s0, s0, 0x8000
	s_addc_u32 s1, s1, 0
	s_add_i32 s2, s36, 1
	s_mul_hi_u32 s33, s2, 0x2c00000
	s_mul_i32 s34, s2, 0x2c00000
	s_mul_hi_u32 s35, s2, 0x1600000
	s_mul_i32 s50, s2, 0x1600000
	s_lshl_b32 s6, s2, 11
	s_mov_b32 s7, s3
	s_lshl_b64 s[8:9], s[2:3], 24
	s_lshl_b64 s[10:11], s[2:3], 23
	s_mul_hi_u32 s51, s2, 0xc00000
	s_mul_i32 s52, s2, 0xc00000
	s_mul_hi_u32 s53, s2, 0x7280000
	s_mul_i32 s54, s2, 0x7280000
	s_mul_hi_u32 s55, s2, 0x3a00000
	v_writelane_b32 v254, s2, 53
	v_mov_b32_e32 v2, v0
	s_mul_i32 s56, s2, 0x3a00000
	v_writelane_b32 v254, s3, 54
	s_waitcnt vmcnt(0) lgkmcnt(0)
	s_barrier
	s_movk_i32 s2, 0x4200
	v_lshrrev_b32_e32 v1, 6, v2
	v_and_b32_e32 v3, 63, v2
	v_readfirstlane_b32 s100, v1
	v_readlane_b32 s101, v252, 0
	s_sub_u32 s101, s101, 128
	s_lshl_b32 s101, s101, 3
	s_add_u32 s100, s100, s101
	s_lshl_b32 s100, s100, 1
	s_add_u32 s100, s100, 0x1800
	v_mul_lo_u32 v1, v1, s2
	v_cmp_eq_u32_e64 s[40:41], 0, v3
	v_add_u32_e32 v3, 0, v1
	v_lshlrev_b32_e32 v1, 2, v2
	v_and_b32_e32 v66, 28, v1
	v_bfe_u32 v1, v2, 3, 3
	v_lshlrev_b32_e32 v2, 3, v2
	v_and_b32_e32 v68, 56, v2
	v_lshl_add_u32 v4, v66, 2, v3
	v_mul_u32_u24_e32 v5, 0x84, v1
	v_mul_u32_u24_e32 v2, 0x84, v68
	v_lshlrev_b32_e32 v6, 2, v1
	v_or_b32_e32 v67, 8, v1
	v_or_b32_e32 v69, 16, v1
	v_or_b32_e32 v71, 24, v1
	v_or_b32_e32 v73, 32, v1
	v_or_b32_e32 v75, 40, v1
	v_or_b32_e32 v77, 48, v1
	v_or_b32_e32 v79, 56, v1
	v_add3_u32 v81, v3, v2, v6
	s_mov_b32 s57, 0x1
	v_add_u32_e32 v83, v4, v5
	s_branch .LBB0_1381

;     __device__ __forceinline__ const float* in(int i) const { return (const float*)(const GAS float*)raw(i); }
;     __device__ __forceinline__ unsigned char* ws() const { return (unsigned char*)(GAS unsigned char*)raw(N_INPUTS + 1); }
; __device__ __forceinline__ CvItem cv_decode(const PT& a, int l, int r) {
;     unsigned char* ws = a.ws(); CvItem it;
;     if (r < IT_WIN) { const int kb = r / 458, nb = r % 458, n0 = nb * 32;
;         int drow; if (n0 < 2048) drow = n0; else if (n0 < 5120) drow = NIN_MAIN + (n0 - 2048); else if (n0 < 8512) drow = 2048 + (n0 - 5120); else drow = 5632 + (n0 - 8512);
;         it = CvItem{a.in(I_W_IN) + (size_t)l * D * NIN, NIN, kb * 64, n0, (bf16_t*)(ws + WS_WIN + l * WIN_L), D, drow, a.in(I_NORM_MIX_G) + l * D}; return it; }
;     for (int it = 0; it < budget; ++it) {
;         unsigned r = 0; if (lane == 0) r = __hip_atomic_fetch_add(ctr, 2u, __ATOMIC_RELAXED, __HIP_MEMORY_SCOPE_AGENT);
;         r = (unsigned)__builtin_amdgcn_readfirstlane((int)r) + (unsigned)CV_PRO_ITEMS;
;         if (r >= (unsigned)IT_LAYER) break;
;         cv_pair(a, lds, l, (int)r, wave, lane);
;     }
; }
.LBB0_1381:
	s_mov_b32 s24, s100
	s_add_u32 s100, s100, 0x800
	s_add_i32 s24, s24, 0xffffd800
	s_cmp_lt_u32 s24, 0xffff70c0
	s_mov_b64 s[2:3], -1
	s_cbranch_scc1 .LBB0_1380
	v_mov_b32_e32 v2, 0x23a60
	s_add_i32 s15, s24, 0x8f40
	v_add_u32_e32 v2, 0, v2
	ds_read_b64 v[2:3], v2
	s_cmpk_gt_u32 s15, 0x393f
	s_waitcnt lgkmcnt(0)
	v_readfirstlane_b32 s20, v3
	v_readfirstlane_b32 s21, v2
	s_cbranch_scc0 .LBB0_1399
	s_cmpk_gt_u32 s15, 0x453f
	s_cbranch_scc0 .LBB0_1396
	s_cmpk_gt_u32 s15, 0x4d3f
	s_mov_b64 s[18:19], -1
	s_cbranch_scc0 .LBB0_1393
	s_cmpk_gt_u32 s15, 0x793f
	s_cbranch_scc0 .LBB0_1391
	v_mov_b32_e32 v2, 0x23a48
	s_and_b32 s2, s15, 0x7fffffc0
	v_add_u32_e32 v2, 0, v2
	ds_read_b64 v[2:3], v2
	s_add_i32 s14, s2, 0xffff86c0
	s_waitcnt lgkmcnt(0)
	v_readfirstlane_b32 s3, v2
	v_readfirstlane_b32 s2, v3
	s_add_u32 s30, s3, s34
	s_addc_u32 s31, s2, s33
	s_lshl_b32 s2, s15, 5
	s_and_b32 s25, s2, 0x7e0
	s_add_u32 s2, s21, s50
	s_addc_u32 s3, s20, s35
	s_add_u32 s12, s2, 0x1ea00000
	s_addc_u32 s13, s3, 0
	s_mov_b64 s[2:3], 0

; __device__ __forceinline__ unsigned cvt_pk_bf16(float lo, float hi) { unsigned r; asm volatile("v_cvt_pk_bf16_f32 %0, %1, %2" : "=v"(r) : "v"(lo), "v"(hi)); return r; }
;     __device__ __forceinline__ void operator()(f32x4 (&acc)[2][2][4][2], const Unit& u, int wr, int wc, int fr, int fq) const {
;         const int row0 = u.pm * BM + wr * 64 + fr; const int col0 = u.pn * BM + wc * 32 + 8 * fq;
; #pragma unroll
;         for (int ai = 0; ai < 2; ++ai)
; #pragma unroll
;             for (int m = 0; m < 4; ++m) { const int row = row0 + ai * HALF + m * 16; float* rowp = X + (size_t)row * ldc + col0; const float* rowi = Xi + (size_t)row * ldc + col0; bf16_t* rowb = XB + (size_t)row * ldc + col0;
;                 float sq = 0.f;
; #pragma unroll
;                 for (int bj = 0; bj < 2; ++bj) { f32x4* p = (f32x4*)(rowp + bj * HALF); const f32x4* pi = (const f32x4*)(rowi + bj * HALF); const f32x4 x0 = pi[0] + acc[ai][bj][m][0], x1 = pi[1] + acc[ai][bj][m][1];
;                     p[0] = x0; p[1] = x1;
;                     u32x4 w; w.x = cvt_pk_bf16(x0[0], x0[1]); w.y = cvt_pk_bf16(x0[2], x0[3]); w.z = cvt_pk_bf16(x1[0], x1[1]); w.w = cvt_pk_bf16(x1[2], x1[3]);
;                     *(u32x4*)(rowb + bj * HALF) = w;
;                     sq += (x0[0] * x0[0] + x0[1] * x0[1]) + (x0[2] * x0[2] + x0[3] * x0[3]) + (x1[0] * x1[0] + x1[1] * x1[1]) + (x1[2] * x1[2] + x1[3] * x1[3]); }
;                 sq += __shfl_xor(sq, 16); sq += __shfl_xor(sq, 32);
;                 if (fq == 0) ss[(size_t)row * 32 + u.pn * 4 + wc] = sq; }
;     }
.LBB0_1750:
	v_lshl_add_u32 v158, s24, 8, v1
	v_lshl_or_b32 v154, s4, 8, v161
	v_ashrrev_i32_e32 v159, 31, v158
	v_ashrrev_i32_e32 v155, 31, v154
	v_lshlrev_b64 v[130:131], 13, v[158:159]
	v_lshlrev_b64 v[156:157], 2, v[154:155]
	v_lshl_add_u64 v[134:135], s[0:1], 0, v[130:131]
	v_lshl_add_u64 v[134:135], v[134:135], 0, v[156:157]
	v_mov_b64_e32 v[248:249], v[134:135]
	global_load_dwordx4 v[176:179], v[248:249], off
	global_load_dwordx4 v[180:183], v[248:249], off offset:16
	global_load_dwordx4 v[184:187], v[248:249], off offset:512
	global_load_dwordx4 v[188:191], v[248:249], off offset:528
	s_mov_b64 s[100:101], 0x20000
	v_lshl_add_u64 v[250:251], v[248:249], 0, s[100:101]
	global_load_dwordx4 v[192:195], v[250:251], off
	global_load_dwordx4 v[196:199], v[250:251], off offset:16
	global_load_dwordx4 v[200:203], v[250:251], off offset:512
	global_load_dwordx4 v[204:207], v[250:251], off offset:528
	s_mov_b64 s[100:101], 0x40000
	v_lshl_add_u64 v[250:251], v[248:249], 0, s[100:101]
	global_load_dwordx4 v[232:235], v[250:251], off
	global_load_dwordx4 v[236:239], v[250:251], off offset:16
	global_load_dwordx4 v[240:243], v[250:251], off offset:512
	global_load_dwordx4 v[244:247], v[250:251], off offset:528
	s_nop 1
	v_readlane_b32 s2, v254, 57
	v_lshlrev_b64 v[140:141], 12, v[158:159]
	v_readlane_b32 s3, v254, 58
	v_lshl_add_u64 v[130:131], s[8:9], 0, v[130:131]
	v_lshl_add_u64 v[130:131], v[130:131], 0, v[156:157]
	v_lshl_add_u64 v[140:141], s[2:3], 0, v[140:141]
	v_lshl_add_u64 v[140:141], v[154:155], 1, v[140:141]
	s_waitcnt vmcnt(10)
	s_nop 1
	v_mov_b64_e32 v[164:165], v[176:177]
	v_mov_b64_e32 v[166:167], v[178:179]
	v_mov_b64_e32 v[168:169], v[180:181]
	v_mov_b64_e32 v[170:171], v[182:183]
	v_pk_add_f32 v[128:129], v[128:129], v[166:167]
	v_pk_add_f32 v[126:127], v[126:127], v[164:165]
	v_pk_add_f32 v[166:167], v[124:125], v[170:171]
	v_pk_add_f32 v[164:165], v[122:123], v[168:169]
	global_store_dwordx4 v[130:131], v[126:129], off
	global_store_dwordx4 v[130:131], v[164:167], off offset:16
	v_cvt_pk_bf16_f32 v122, v126, v127
	v_cvt_pk_bf16_f32 v123, v128, v129
	v_cvt_pk_bf16_f32 v124, v164, v165
	v_cvt_pk_bf16_f32 v125, v166, v167
	global_store_dwordx4 v[140:141], v[122:125], off
	s_nop 1
	v_mul_f32_e32 v124, v127, v127
	v_mul_f32_e32 v125, v129, v129
	v_mul_f32_e32 v127, v165, v165
	v_fmac_f32_e32 v124, v126, v126
	v_fmac_f32_e32 v125, v128, v128
	v_mul_f32_e32 v129, v167, v167
	v_fmac_f32_e32 v127, v164, v164
	v_add_f32_e32 v124, v124, v125
	v_fmac_f32_e32 v129, v166, v166
	v_add_f32_e32 v124, v124, v127
	v_add_f32_e32 v128, v129, v124
	v_and_b32_e32 v123, 64, v223
	v_xor_b32_e32 v122, 16, v223
	v_add_u32_e32 v123, 64, v123
	v_cmp_lt_i32_e32 vcc, v122, v123
	v_xor_b32_e32 v134, 32, v223
	s_waitcnt vmcnt(11)
	s_nop 1
	v_mov_b64_e32 v[168:169], v[184:185]
	v_mov_b64_e32 v[170:171], v[186:187]
	v_mov_b64_e32 v[172:173], v[188:189]
	v_mov_b64_e32 v[174:175], v[190:191]
	s_mov_b64 s[100:101], 0x60000
	v_lshl_add_u64 v[250:251], v[248:249], 0, s[100:101]
	global_load_dwordx4 v[176:179], v[250:251], off
	global_load_dwordx4 v[180:183], v[250:251], off offset:16
	global_load_dwordx4 v[184:187], v[250:251], off offset:512
	global_load_dwordx4 v[188:191], v[250:251], off offset:528
	v_pk_add_f32 v[120:121], v[120:121], v[170:171]
	v_pk_add_f32 v[118:119], v[118:119], v[168:169]
	v_pk_add_f32 v[124:125], v[114:115], v[172:173]
	v_mul_f32_e32 v114, v119, v119
	v_mul_f32_e32 v115, v121, v121
	v_pk_add_f32 v[126:127], v[116:117], v[174:175]
	v_mul_f32_e32 v116, v125, v125
	v_fmac_f32_e32 v114, v118, v118
	v_fmac_f32_e32 v115, v120, v120
	v_mul_f32_e32 v117, v127, v127
	v_fmac_f32_e32 v116, v124, v124
	v_add_f32_e32 v114, v114, v115
	v_fmac_f32_e32 v117, v126, v126
	v_add_f32_e32 v114, v114, v116
	v_cndmask_b32_e32 v122, v223, v122, vcc
	v_add_f32_e32 v114, v117, v114
	v_lshlrev_b32_e32 v122, 2, v122
	v_add_f32_e32 v114, v128, v114
	ds_bpermute_b32 v115, v122, v114
	v_cmp_lt_i32_e32 vcc, v134, v123
	global_store_dwordx4 v[130:131], v[118:121], off offset:512
	global_store_dwordx4 v[130:131], v[124:127], off offset:528
	v_cndmask_b32_e32 v116, v223, v134, vcc
	v_lshlrev_b32_e32 v116, 2, v116
	s_waitcnt lgkmcnt(0)
	v_add_f32_e32 v114, v114, v115
	ds_bpermute_b32 v115, v116, v114
	v_cvt_pk_bf16_f32 v118, v118, v119
	v_cvt_pk_bf16_f32 v119, v120, v121
	v_cvt_pk_bf16_f32 v120, v124, v125
	v_cvt_pk_bf16_f32 v121, v126, v127
	global_store_dwordx4 v[140:141], v[118:121], off offset:256
	s_and_saveexec_b64 s[2:3], s[42:43]
	s_cbranch_execz .LBB0_1752
	s_waitcnt lgkmcnt(0)
	v_add_f32_e32 v117, v114, v115
	s_lshl_b32 s26, s4, 2
	v_lshlrev_b64 v[114:115], 7, v[158:159]
	s_ashr_i32 s27, s26, 31
	v_lshl_add_u64 v[114:115], s[10:11], 0, v[114:115]
	v_lshl_add_u64 v[114:115], s[26:27], 2, v[114:115]
	v_readlane_b32 s26, v254, 53
	v_readlane_b32 s27, v254, 54
	s_mov_b32 s15, s27
	s_lshl_b32 s26, s46, 2
	v_writelane_b32 v254, s14, 53
	v_lshl_add_u64 v[114:115], v[114:115], 0, s[26:27]
	global_store_dword v[114:115], v117, off
	v_writelane_b32 v254, s15, 54
; __device__ __forceinline__ unsigned cvt_pk_bf16(float lo, float hi) { unsigned r; asm volatile("v_cvt_pk_bf16_f32 %0, %1, %2" : "=v"(r) : "v"(lo), "v"(hi)); return r; }
;     __device__ __forceinline__ void operator()(f32x4 (&acc)[2][2][4][2], const Unit& u, int wr, int wc, int fr, int fq) const {
;         const int row0 = u.pm * BM + wr * 64 + fr; const int col0 = u.pn * BM + wc * 32 + 8 * fq;
; #pragma unroll
;         for (int ai = 0; ai < 2; ++ai)
; #pragma unroll
;             for (int m = 0; m < 4; ++m) { const int row = row0 + ai * HALF + m * 16; float* rowp = X + (size_t)row * ldc + col0; const float* rowi = Xi + (size_t)row * ldc + col0; bf16_t* rowb = XB + (size_t)row * ldc + col0;
;                 float sq = 0.f;
; #pragma unroll
;                 for (int bj = 0; bj < 2; ++bj) { f32x4* p = (f32x4*)(rowp + bj * HALF); const f32x4* pi = (const f32x4*)(rowi + bj * HALF); const f32x4 x0 = pi[0] + acc[ai][bj][m][0], x1 = pi[1] + acc[ai][bj][m][1];
;                     p[0] = x0; p[1] = x1;
;                     u32x4 w; w.x = cvt_pk_bf16(x0[0], x0[1]); w.y = cvt_pk_bf16(x0[2], x0[3]); w.z = cvt_pk_bf16(x1[0], x1[1]); w.w = cvt_pk_bf16(x1[2], x1[3]);
;                     *(u32x4*)(rowb + bj * HALF) = w;
;                     sq += (x0[0] * x0[0] + x0[1] * x0[1]) + (x0[2] * x0[2] + x0[3] * x0[3]) + (x1[0] * x1[0] + x1[1] * x1[1]) + (x1[2] * x1[2] + x1[3] * x1[3]); }
;                 sq += __shfl_xor(sq, 16); sq += __shfl_xor(sq, 32);
;                 if (fq == 0) ss[(size_t)row * 32 + u.pn * 4 + wc] = sq; }
;     }
.LBB0_1752:
	s_or_b64 exec, exec, s[2:3]
	v_or_b32_e32 v114, 16, v158
	s_waitcnt lgkmcnt(0)
	v_ashrrev_i32_e32 v115, 31, v114
	v_lshlrev_b64 v[128:129], 13, v[114:115]
	v_lshl_add_u64 v[118:119], s[0:1], 0, v[128:129]
	v_lshl_add_u64 v[130:131], v[118:119], 0, v[156:157]
	s_nop 1
	v_readlane_b32 s2, v254, 57
	v_lshlrev_b64 v[134:135], 12, v[114:115]
	v_readlane_b32 s3, v254, 58
	v_lshl_add_u64 v[128:129], s[8:9], 0, v[128:129]
	v_lshl_add_u64 v[128:129], v[128:129], 0, v[156:157]
	v_lshl_add_u64 v[134:135], s[2:3], 0, v[134:135]
	v_lshl_add_u64 v[134:135], v[154:155], 1, v[134:135]
	s_waitcnt vmcnt(17)
	s_nop 1
	v_mov_b64_e32 v[118:119], v[192:193]
	v_mov_b64_e32 v[120:121], v[194:195]
	v_mov_b64_e32 v[124:125], v[196:197]
	v_mov_b64_e32 v[126:127], v[198:199]
	v_pk_add_f32 v[112:113], v[112:113], v[120:121]
	v_pk_add_f32 v[110:111], v[110:111], v[118:119]
	v_pk_add_f32 v[108:109], v[108:109], v[126:127]
	v_pk_add_f32 v[106:107], v[106:107], v[124:125]
	global_store_dwordx4 v[128:129], v[110:113], off
	global_store_dwordx4 v[128:129], v[106:109], off offset:16
	v_cvt_pk_bf16_f32 v118, v110, v111
	v_cvt_pk_bf16_f32 v119, v112, v113
	v_cvt_pk_bf16_f32 v120, v106, v107
	v_cvt_pk_bf16_f32 v121, v108, v109
	global_store_dwordx4 v[134:135], v[118:121], off
	s_nop 1
	v_mul_f32_e32 v111, v111, v111
	v_mul_f32_e32 v113, v113, v113
	v_mul_f32_e32 v107, v107, v107
	v_fmac_f32_e32 v111, v110, v110
	v_fmac_f32_e32 v113, v112, v112
	v_mul_f32_e32 v109, v109, v109
	v_fmac_f32_e32 v107, v106, v106
	v_add_f32_e32 v106, v111, v113
	v_fmac_f32_e32 v109, v108, v108
	v_add_f32_e32 v106, v106, v107
	v_add_f32_e32 v110, v109, v106
	s_waitcnt vmcnt(18)
	s_nop 1
	v_mov_b64_e32 v[118:119], v[200:201]
	v_mov_b64_e32 v[120:121], v[202:203]
	v_mov_b64_e32 v[124:125], v[204:205]
	v_mov_b64_e32 v[126:127], v[206:207]
	s_mov_b64 s[100:101], 0x100000
	v_lshl_add_u64 v[250:251], v[248:249], 0, s[100:101]
	global_load_dwordx4 v[192:195], v[250:251], off
	global_load_dwordx4 v[196:199], v[250:251], off offset:16
	global_load_dwordx4 v[200:203], v[250:251], off offset:512
	global_load_dwordx4 v[204:207], v[250:251], off offset:528
	v_pk_add_f32 v[104:105], v[104:105], v[120:121]
	v_pk_add_f32 v[102:103], v[102:103], v[118:119]
	v_pk_add_f32 v[106:107], v[98:99], v[124:125]
	v_mul_f32_e32 v98, v103, v103
	v_mul_f32_e32 v99, v105, v105
	v_pk_add_f32 v[108:109], v[100:101], v[126:127]
	v_mul_f32_e32 v100, v107, v107
	v_fmac_f32_e32 v98, v102, v102
	v_fmac_f32_e32 v99, v104, v104
	v_mul_f32_e32 v101, v109, v109
	v_fmac_f32_e32 v100, v106, v106
	v_add_f32_e32 v98, v98, v99
	v_add_f32_e32 v98, v98, v100
	v_fmac_f32_e32 v101, v108, v108
	v_add_f32_e32 v98, v101, v98
	v_add_f32_e32 v98, v110, v98
	ds_bpermute_b32 v99, v122, v98
	global_store_dwordx4 v[128:129], v[102:105], off offset:512
	global_store_dwordx4 v[128:129], v[106:109], off offset:528
	v_cvt_pk_bf16_f32 v100, v102, v103
	v_cvt_pk_bf16_f32 v101, v104, v105
	s_waitcnt lgkmcnt(0)
	v_add_f32_e32 v98, v98, v99
	ds_bpermute_b32 v99, v116, v98
	v_cvt_pk_bf16_f32 v102, v106, v107
	v_cvt_pk_bf16_f32 v103, v108, v109
	global_store_dwordx4 v[134:135], v[100:103], off offset:256
	s_and_saveexec_b64 s[2:3], s[42:43]
	s_cbranch_execz .LBB0_1754
	s_waitcnt lgkmcnt(0)
	v_add_f32_e32 v100, v98, v99
	s_lshl_b32 s26, s4, 2
	v_lshlrev_b64 v[98:99], 7, v[114:115]
	s_ashr_i32 s27, s26, 31
	v_lshl_add_u64 v[98:99], s[10:11], 0, v[98:99]
	v_lshl_add_u64 v[98:99], s[26:27], 2, v[98:99]
	v_readlane_b32 s26, v254, 53
	v_readlane_b32 s27, v254, 54
	s_mov_b32 s15, s27
	s_lshl_b32 s26, s46, 2
	v_writelane_b32 v254, s14, 53
	v_lshl_add_u64 v[98:99], v[98:99], 0, s[26:27]
	global_store_dword v[98:99], v100, off
	v_writelane_b32 v254, s15, 54
.LBB0_1754:
	s_or_b64 exec, exec, s[2:3]
	v_or_b32_e32 v98, 32, v158
	s_waitcnt lgkmcnt(0)
	v_ashrrev_i32_e32 v99, 31, v98
	v_lshlrev_b64 v[108:109], 13, v[98:99]
	v_lshl_add_u64 v[100:101], s[0:1], 0, v[108:109]
	v_lshl_add_u64 v[110:111], v[100:101], 0, v[156:157]
	s_nop 1
	v_readlane_b32 s2, v254, 57
	v_lshlrev_b64 v[112:113], 12, v[98:99]
	v_readlane_b32 s3, v254, 58
	v_lshl_add_u64 v[108:109], s[8:9], 0, v[108:109]
	v_lshl_add_u64 v[108:109], v[108:109], 0, v[156:157]
	v_lshl_add_u64 v[112:113], s[2:3], 0, v[112:113]
	v_lshl_add_u64 v[112:113], v[154:155], 1, v[112:113]
	s_waitcnt vmcnt(24)
	s_nop 1
	v_mov_b64_e32 v[100:101], v[232:233]
	v_mov_b64_e32 v[102:103], v[234:235]
	v_mov_b64_e32 v[104:105], v[236:237]
	v_mov_b64_e32 v[106:107], v[238:239]
	v_pk_add_f32 v[96:97], v[96:97], v[102:103]
	v_pk_add_f32 v[94:95], v[94:95], v[100:101]
	v_pk_add_f32 v[92:93], v[92:93], v[106:107]
	v_pk_add_f32 v[90:91], v[90:91], v[104:105]
	global_store_dwordx4 v[108:109], v[94:97], off
	global_store_dwordx4 v[108:109], v[90:93], off offset:16
	v_cvt_pk_bf16_f32 v100, v94, v95
	v_cvt_pk_bf16_f32 v101, v96, v97
	v_cvt_pk_bf16_f32 v102, v90, v91
	v_cvt_pk_bf16_f32 v103, v92, v93
	global_store_dwordx4 v[112:113], v[100:103], off
	s_nop 1
	v_mul_f32_e32 v95, v95, v95
	v_mul_f32_e32 v97, v97, v97
	v_mul_f32_e32 v91, v91, v91
	v_fmac_f32_e32 v95, v94, v94
	v_fmac_f32_e32 v97, v96, v96
	v_mul_f32_e32 v93, v93, v93
	v_fmac_f32_e32 v91, v90, v90
	v_add_f32_e32 v90, v95, v97
	v_fmac_f32_e32 v93, v92, v92
	v_add_f32_e32 v90, v90, v91
	v_add_f32_e32 v94, v93, v90
	s_waitcnt vmcnt(25)
	s_nop 1
	v_mov_b64_e32 v[100:101], v[240:241]
	v_mov_b64_e32 v[102:103], v[242:243]
	v_mov_b64_e32 v[104:105], v[244:245]
	v_mov_b64_e32 v[106:107], v[246:247]
	s_mov_b64 s[100:101], 0x120000
	v_lshl_add_u64 v[250:251], v[248:249], 0, s[100:101]
	global_load_dwordx4 v[232:235], v[250:251], off
	global_load_dwordx4 v[236:239], v[250:251], off offset:16
	global_load_dwordx4 v[240:243], v[250:251], off offset:512
	global_load_dwordx4 v[244:247], v[250:251], off offset:528
	v_pk_add_f32 v[88:89], v[88:89], v[102:103]
	v_pk_add_f32 v[86:87], v[86:87], v[100:101]
	v_pk_add_f32 v[90:91], v[82:83], v[104:105]
	v_mul_f32_e32 v82, v87, v87
	v_mul_f32_e32 v83, v89, v89
	v_pk_add_f32 v[92:93], v[84:85], v[106:107]
	v_mul_f32_e32 v84, v91, v91
	v_fmac_f32_e32 v82, v86, v86
	v_fmac_f32_e32 v83, v88, v88
	v_mul_f32_e32 v85, v93, v93
	v_fmac_f32_e32 v84, v90, v90
	v_add_f32_e32 v82, v82, v83
	v_add_f32_e32 v82, v82, v84
	v_fmac_f32_e32 v85, v92, v92
	v_add_f32_e32 v82, v85, v82
	v_add_f32_e32 v82, v94, v82
	ds_bpermute_b32 v83, v122, v82
	global_store_dwordx4 v[108:109], v[86:89], off offset:512
	global_store_dwordx4 v[108:109], v[90:93], off offset:528
	v_cvt_pk_bf16_f32 v84, v86, v87
	v_cvt_pk_bf16_f32 v85, v88, v89
	s_waitcnt lgkmcnt(0)
	v_add_f32_e32 v82, v82, v83
	ds_bpermute_b32 v83, v116, v82
	v_cvt_pk_bf16_f32 v86, v90, v91
	v_cvt_pk_bf16_f32 v87, v92, v93
	global_store_dwordx4 v[112:113], v[84:87], off offset:256
	s_and_saveexec_b64 s[2:3], s[42:43]
	s_cbranch_execz .LBB0_1756
; __device__ __forceinline__ unsigned cvt_pk_bf16(float lo, float hi) { unsigned r; asm volatile("v_cvt_pk_bf16_f32 %0, %1, %2" : "=v"(r) : "v"(lo), "v"(hi)); return r; }
;     __device__ __forceinline__ void operator()(f32x4 (&acc)[2][2][4][2], const Unit& u, int wr, int wc, int fr, int fq) const {
;         const int row0 = u.pm * BM + wr * 64 + fr; const int col0 = u.pn * BM + wc * 32 + 8 * fq;
; #pragma unroll
;         for (int ai = 0; ai < 2; ++ai)
; #pragma unroll
;             for (int m = 0; m < 4; ++m) { const int row = row0 + ai * HALF + m * 16; float* rowp = X + (size_t)row * ldc + col0; const float* rowi = Xi + (size_t)row * ldc + col0; bf16_t* rowb = XB + (size_t)row * ldc + col0;
;                 float sq = 0.f;
; #pragma unroll
;                 for (int bj = 0; bj < 2; ++bj) { f32x4* p = (f32x4*)(rowp + bj * HALF); const f32x4* pi = (const f32x4*)(rowi + bj * HALF); const f32x4 x0 = pi[0] + acc[ai][bj][m][0], x1 = pi[1] + acc[ai][bj][m][1];
;                     p[0] = x0; p[1] = x1;
;                     u32x4 w; w.x = cvt_pk_bf16(x0[0], x0[1]); w.y = cvt_pk_bf16(x0[2], x0[3]); w.z = cvt_pk_bf16(x1[0], x1[1]); w.w = cvt_pk_bf16(x1[2], x1[3]);
;                     *(u32x4*)(rowb + bj * HALF) = w;
;                     sq += (x0[0] * x0[0] + x0[1] * x0[1]) + (x0[2] * x0[2] + x0[3] * x0[3]) + (x1[0] * x1[0] + x1[1] * x1[1]) + (x1[2] * x1[2] + x1[3] * x1[3]); }
;                 sq += __shfl_xor(sq, 16); sq += __shfl_xor(sq, 32);
;                 if (fq == 0) ss[(size_t)row * 32 + u.pn * 4 + wc] = sq; }
;     }
	s_waitcnt lgkmcnt(0)
	v_add_f32_e32 v84, v82, v83
	s_lshl_b32 s26, s4, 2
	v_lshlrev_b64 v[82:83], 7, v[98:99]
	s_ashr_i32 s27, s26, 31
	v_lshl_add_u64 v[82:83], s[10:11], 0, v[82:83]
	v_lshl_add_u64 v[82:83], s[26:27], 2, v[82:83]
	v_readlane_b32 s26, v254, 53
	v_readlane_b32 s27, v254, 54
	s_mov_b32 s15, s27
	s_lshl_b32 s26, s46, 2
	v_writelane_b32 v254, s14, 53
	v_lshl_add_u64 v[82:83], v[82:83], 0, s[26:27]
	global_store_dword v[82:83], v84, off
	v_writelane_b32 v254, s15, 54
.LBB0_1756:
	s_or_b64 exec, exec, s[2:3]
	v_or_b32_e32 v82, 48, v158
	s_waitcnt lgkmcnt(0)
	v_ashrrev_i32_e32 v83, 31, v82
	v_lshlrev_b64 v[92:93], 13, v[82:83]
	v_lshl_add_u64 v[84:85], s[0:1], 0, v[92:93]
	v_lshl_add_u64 v[94:95], v[84:85], 0, v[156:157]
	s_nop 1
	v_readlane_b32 s2, v254, 57
	v_lshlrev_b64 v[96:97], 12, v[82:83]
	v_readlane_b32 s3, v254, 58
	v_lshl_add_u64 v[92:93], s[8:9], 0, v[92:93]
	v_lshl_add_u64 v[92:93], v[92:93], 0, v[156:157]
	v_lshl_add_u64 v[96:97], s[2:3], 0, v[96:97]
	v_lshl_add_u64 v[96:97], v[154:155], 1, v[96:97]
	s_waitcnt vmcnt(28)
	s_nop 1
	v_mov_b64_e32 v[84:85], v[176:177]
	v_mov_b64_e32 v[86:87], v[178:179]
	v_mov_b64_e32 v[88:89], v[180:181]
	v_mov_b64_e32 v[90:91], v[182:183]
	v_pk_add_f32 v[80:81], v[80:81], v[86:87]
	v_pk_add_f32 v[78:79], v[78:79], v[84:85]
	v_pk_add_f32 v[76:77], v[76:77], v[90:91]
	v_pk_add_f32 v[74:75], v[74:75], v[88:89]
	global_store_dwordx4 v[92:93], v[78:81], off
	global_store_dwordx4 v[92:93], v[74:77], off offset:16
	v_cvt_pk_bf16_f32 v84, v78, v79
	v_cvt_pk_bf16_f32 v85, v80, v81
	v_cvt_pk_bf16_f32 v86, v74, v75
	v_cvt_pk_bf16_f32 v87, v76, v77
	global_store_dwordx4 v[96:97], v[84:87], off
	s_nop 1
	v_mul_f32_e32 v79, v79, v79
	v_mul_f32_e32 v81, v81, v81
	v_mul_f32_e32 v75, v75, v75
	v_fmac_f32_e32 v79, v78, v78
	v_fmac_f32_e32 v81, v80, v80
	v_mul_f32_e32 v77, v77, v77
	v_fmac_f32_e32 v75, v74, v74
	v_add_f32_e32 v74, v79, v81
	v_fmac_f32_e32 v77, v76, v76
	v_add_f32_e32 v74, v74, v75
	v_add_f32_e32 v78, v77, v74
	s_waitcnt vmcnt(29)
	s_nop 1
	v_mov_b64_e32 v[84:85], v[184:185]
	v_mov_b64_e32 v[86:87], v[186:187]
	v_mov_b64_e32 v[88:89], v[188:189]
	v_mov_b64_e32 v[90:91], v[190:191]
	s_mov_b64 s[100:101], 0x140000
	v_lshl_add_u64 v[250:251], v[248:249], 0, s[100:101]
	global_load_dwordx4 v[176:179], v[250:251], off
	global_load_dwordx4 v[180:183], v[250:251], off offset:16
	global_load_dwordx4 v[184:187], v[250:251], off offset:512
	global_load_dwordx4 v[188:191], v[250:251], off offset:528
	v_pk_add_f32 v[72:73], v[72:73], v[86:87]
	v_pk_add_f32 v[70:71], v[70:71], v[84:85]
	v_pk_add_f32 v[74:75], v[66:67], v[88:89]
	v_mul_f32_e32 v66, v71, v71
	v_mul_f32_e32 v67, v73, v73
	v_pk_add_f32 v[76:77], v[68:69], v[90:91]
	v_mul_f32_e32 v68, v75, v75
	v_fmac_f32_e32 v66, v70, v70
	v_fmac_f32_e32 v67, v72, v72
	v_mul_f32_e32 v69, v77, v77
	v_fmac_f32_e32 v68, v74, v74
	v_add_f32_e32 v66, v66, v67
	v_add_f32_e32 v66, v66, v68
	v_fmac_f32_e32 v69, v76, v76
	v_add_f32_e32 v66, v69, v66
	v_add_f32_e32 v66, v78, v66
	ds_bpermute_b32 v67, v122, v66
	global_store_dwordx4 v[92:93], v[70:73], off offset:512
	global_store_dwordx4 v[92:93], v[74:77], off offset:528
	v_cvt_pk_bf16_f32 v68, v70, v71
	v_cvt_pk_bf16_f32 v69, v72, v73
	s_waitcnt lgkmcnt(0)
	v_add_f32_e32 v66, v66, v67
	ds_bpermute_b32 v67, v116, v66
	v_cvt_pk_bf16_f32 v70, v74, v75
	v_cvt_pk_bf16_f32 v71, v76, v77
	global_store_dwordx4 v[96:97], v[68:71], off offset:256
	s_and_saveexec_b64 s[2:3], s[42:43]
	s_cbranch_execz .LBB0_1758
	s_waitcnt lgkmcnt(0)
	v_add_f32_e32 v68, v66, v67
	s_lshl_b32 s26, s4, 2
	v_lshlrev_b64 v[66:67], 7, v[82:83]
	s_ashr_i32 s27, s26, 31
	v_lshl_add_u64 v[66:67], s[10:11], 0, v[66:67]
	v_lshl_add_u64 v[66:67], s[26:27], 2, v[66:67]
	v_readlane_b32 s26, v254, 53
	v_readlane_b32 s27, v254, 54
	s_mov_b32 s15, s27
	s_lshl_b32 s26, s46, 2
	v_writelane_b32 v254, s14, 53
	v_lshl_add_u64 v[66:67], v[66:67], 0, s[26:27]
	global_store_dword v[66:67], v68, off
	v_writelane_b32 v254, s15, 54
.LBB0_1758:
	s_or_b64 exec, exec, s[2:3]
	v_add_u32_e32 v66, 0x80, v158
	s_waitcnt lgkmcnt(0)
	v_ashrrev_i32_e32 v67, 31, v66
	v_lshlrev_b64 v[76:77], 13, v[66:67]
	v_lshl_add_u64 v[68:69], s[0:1], 0, v[76:77]
	v_lshl_add_u64 v[78:79], v[68:69], 0, v[156:157]
	s_nop 1
	v_readlane_b32 s2, v254, 57
	v_lshlrev_b64 v[80:81], 12, v[66:67]
	v_readlane_b32 s3, v254, 58
	v_lshl_add_u64 v[76:77], s[8:9], 0, v[76:77]
	v_lshl_add_u64 v[76:77], v[76:77], 0, v[156:157]
	v_lshl_add_u64 v[80:81], s[2:3], 0, v[80:81]
	v_lshl_add_u64 v[80:81], v[154:155], 1, v[80:81]
	s_waitcnt vmcnt(28)
	s_nop 1
	v_mov_b64_e32 v[68:69], v[192:193]
	v_mov_b64_e32 v[70:71], v[194:195]
	v_mov_b64_e32 v[72:73], v[196:197]
	v_mov_b64_e32 v[74:75], v[198:199]
	v_pk_add_f32 v[64:65], v[64:65], v[70:71]
	v_pk_add_f32 v[62:63], v[62:63], v[68:69]
	v_pk_add_f32 v[60:61], v[60:61], v[74:75]
	v_pk_add_f32 v[58:59], v[58:59], v[72:73]
	global_store_dwordx4 v[76:77], v[62:65], off
	global_store_dwordx4 v[76:77], v[58:61], off offset:16
	v_cvt_pk_bf16_f32 v68, v62, v63
	v_cvt_pk_bf16_f32 v69, v64, v65
	v_cvt_pk_bf16_f32 v70, v58, v59
	v_cvt_pk_bf16_f32 v71, v60, v61
	global_store_dwordx4 v[80:81], v[68:71], off
	s_nop 1
	v_mul_f32_e32 v63, v63, v63
	v_mul_f32_e32 v65, v65, v65
	v_mul_f32_e32 v59, v59, v59
	v_fmac_f32_e32 v63, v62, v62
	v_fmac_f32_e32 v65, v64, v64
	v_mul_f32_e32 v61, v61, v61
	v_fmac_f32_e32 v59, v58, v58
	v_add_f32_e32 v58, v63, v65
	v_fmac_f32_e32 v61, v60, v60
	v_add_f32_e32 v58, v58, v59
	v_add_f32_e32 v62, v61, v58
	s_waitcnt vmcnt(29)
	s_nop 1
	v_mov_b64_e32 v[68:69], v[200:201]
	v_mov_b64_e32 v[70:71], v[202:203]
	v_mov_b64_e32 v[72:73], v[204:205]
	v_mov_b64_e32 v[74:75], v[206:207]
	s_mov_b64 s[100:101], 0x160000
	v_lshl_add_u64 v[250:251], v[248:249], 0, s[100:101]
	global_load_dwordx4 v[192:195], v[250:251], off
	global_load_dwordx4 v[196:199], v[250:251], off offset:16
	global_load_dwordx4 v[200:203], v[250:251], off offset:512
	global_load_dwordx4 v[204:207], v[250:251], off offset:528
	v_pk_add_f32 v[56:57], v[56:57], v[70:71]
	v_pk_add_f32 v[54:55], v[54:55], v[68:69]
	v_pk_add_f32 v[58:59], v[50:51], v[72:73]
	v_mul_f32_e32 v50, v55, v55
	v_mul_f32_e32 v51, v57, v57
	v_pk_add_f32 v[60:61], v[52:53], v[74:75]
	v_mul_f32_e32 v52, v59, v59
	v_fmac_f32_e32 v50, v54, v54
	v_fmac_f32_e32 v51, v56, v56
	v_mul_f32_e32 v53, v61, v61
	v_fmac_f32_e32 v52, v58, v58
	v_add_f32_e32 v50, v50, v51
	v_add_f32_e32 v50, v50, v52
	v_fmac_f32_e32 v53, v60, v60
	v_add_f32_e32 v50, v53, v50
	v_add_f32_e32 v50, v62, v50
	ds_bpermute_b32 v51, v122, v50
	global_store_dwordx4 v[76:77], v[54:57], off offset:512
	global_store_dwordx4 v[76:77], v[58:61], off offset:528
	v_cvt_pk_bf16_f32 v52, v54, v55
	v_cvt_pk_bf16_f32 v53, v56, v57
	s_waitcnt lgkmcnt(0)
	v_add_f32_e32 v50, v50, v51
	ds_bpermute_b32 v51, v116, v50
	v_cvt_pk_bf16_f32 v54, v58, v59
	v_cvt_pk_bf16_f32 v55, v60, v61
	global_store_dwordx4 v[80:81], v[52:55], off offset:256
	s_and_saveexec_b64 s[2:3], s[42:43]
	s_cbranch_execz .LBB0_1760
; __device__ __forceinline__ unsigned cvt_pk_bf16(float lo, float hi) { unsigned r; asm volatile("v_cvt_pk_bf16_f32 %0, %1, %2" : "=v"(r) : "v"(lo), "v"(hi)); return r; }
;     __device__ __forceinline__ void operator()(f32x4 (&acc)[2][2][4][2], const Unit& u, int wr, int wc, int fr, int fq) const {
;         const int row0 = u.pm * BM + wr * 64 + fr; const int col0 = u.pn * BM + wc * 32 + 8 * fq;
; #pragma unroll
;         for (int ai = 0; ai < 2; ++ai)
; #pragma unroll
;             for (int m = 0; m < 4; ++m) { const int row = row0 + ai * HALF + m * 16; float* rowp = X + (size_t)row * ldc + col0; const float* rowi = Xi + (size_t)row * ldc + col0; bf16_t* rowb = XB + (size_t)row * ldc + col0;
;                 float sq = 0.f;
; #pragma unroll
;                 for (int bj = 0; bj < 2; ++bj) { f32x4* p = (f32x4*)(rowp + bj * HALF); const f32x4* pi = (const f32x4*)(rowi + bj * HALF); const f32x4 x0 = pi[0] + acc[ai][bj][m][0], x1 = pi[1] + acc[ai][bj][m][1];
;                     p[0] = x0; p[1] = x1;
;                     u32x4 w; w.x = cvt_pk_bf16(x0[0], x0[1]); w.y = cvt_pk_bf16(x0[2], x0[3]); w.z = cvt_pk_bf16(x1[0], x1[1]); w.w = cvt_pk_bf16(x1[2], x1[3]);
;                     *(u32x4*)(rowb + bj * HALF) = w;
;                     sq += (x0[0] * x0[0] + x0[1] * x0[1]) + (x0[2] * x0[2] + x0[3] * x0[3]) + (x1[0] * x1[0] + x1[1] * x1[1]) + (x1[2] * x1[2] + x1[3] * x1[3]); }
;                 sq += __shfl_xor(sq, 16); sq += __shfl_xor(sq, 32);
;                 if (fq == 0) ss[(size_t)row * 32 + u.pn * 4 + wc] = sq; }
;     }
	s_waitcnt lgkmcnt(0)
	v_add_f32_e32 v52, v50, v51
	s_lshl_b32 s26, s4, 2
	v_lshlrev_b64 v[50:51], 7, v[66:67]
	s_ashr_i32 s27, s26, 31
	v_lshl_add_u64 v[50:51], s[10:11], 0, v[50:51]
	v_lshl_add_u64 v[50:51], s[26:27], 2, v[50:51]
	v_readlane_b32 s26, v254, 53
	v_readlane_b32 s27, v254, 54
	s_mov_b32 s15, s27
	s_lshl_b32 s26, s46, 2
	v_writelane_b32 v254, s14, 53
	v_lshl_add_u64 v[50:51], v[50:51], 0, s[26:27]
	global_store_dword v[50:51], v52, off
	v_writelane_b32 v254, s15, 54
.LBB0_1760:
	s_or_b64 exec, exec, s[2:3]
	v_add_u32_e32 v50, 0x90, v158
	s_waitcnt lgkmcnt(0)
	v_ashrrev_i32_e32 v51, 31, v50
	v_lshlrev_b64 v[60:61], 13, v[50:51]
	v_lshl_add_u64 v[52:53], s[0:1], 0, v[60:61]
	v_lshl_add_u64 v[62:63], v[52:53], 0, v[156:157]
	s_nop 1
	v_readlane_b32 s2, v254, 57
	v_lshlrev_b64 v[64:65], 12, v[50:51]
	v_readlane_b32 s3, v254, 58
	v_lshl_add_u64 v[60:61], s[8:9], 0, v[60:61]
	v_lshl_add_u64 v[60:61], v[60:61], 0, v[156:157]
	v_lshl_add_u64 v[64:65], s[2:3], 0, v[64:65]
	v_lshl_add_u64 v[64:65], v[154:155], 1, v[64:65]
	s_waitcnt vmcnt(28)
	s_nop 1
	v_mov_b64_e32 v[52:53], v[232:233]
	v_mov_b64_e32 v[54:55], v[234:235]
	v_mov_b64_e32 v[56:57], v[236:237]
	v_mov_b64_e32 v[58:59], v[238:239]
	v_pk_add_f32 v[48:49], v[48:49], v[54:55]
	v_pk_add_f32 v[46:47], v[46:47], v[52:53]
	v_pk_add_f32 v[44:45], v[44:45], v[58:59]
	v_pk_add_f32 v[42:43], v[42:43], v[56:57]
	global_store_dwordx4 v[60:61], v[46:49], off
	global_store_dwordx4 v[60:61], v[42:45], off offset:16
	v_cvt_pk_bf16_f32 v52, v46, v47
	v_cvt_pk_bf16_f32 v53, v48, v49
	v_cvt_pk_bf16_f32 v54, v42, v43
	v_cvt_pk_bf16_f32 v55, v44, v45
	global_store_dwordx4 v[64:65], v[52:55], off
	s_nop 1
	v_mul_f32_e32 v47, v47, v47
	v_mul_f32_e32 v49, v49, v49
	v_mul_f32_e32 v43, v43, v43
	v_fmac_f32_e32 v47, v46, v46
	v_fmac_f32_e32 v49, v48, v48
	v_mul_f32_e32 v45, v45, v45
	v_fmac_f32_e32 v43, v42, v42
	v_add_f32_e32 v42, v47, v49
	v_fmac_f32_e32 v45, v44, v44
	v_add_f32_e32 v42, v42, v43
	v_add_f32_e32 v46, v45, v42
	s_waitcnt vmcnt(29)
	s_nop 1
	v_mov_b64_e32 v[52:53], v[240:241]
	v_mov_b64_e32 v[54:55], v[242:243]
	v_mov_b64_e32 v[56:57], v[244:245]
	v_mov_b64_e32 v[58:59], v[246:247]
	v_pk_add_f32 v[40:41], v[40:41], v[54:55]
	v_pk_add_f32 v[38:39], v[38:39], v[52:53]
	v_pk_add_f32 v[42:43], v[34:35], v[56:57]
	v_mul_f32_e32 v34, v39, v39
	v_mul_f32_e32 v35, v41, v41
	v_pk_add_f32 v[44:45], v[36:37], v[58:59]
	v_mul_f32_e32 v36, v43, v43
	v_fmac_f32_e32 v34, v38, v38
	v_fmac_f32_e32 v35, v40, v40
	v_mul_f32_e32 v37, v45, v45
	v_fmac_f32_e32 v36, v42, v42
	v_add_f32_e32 v34, v34, v35
	v_add_f32_e32 v34, v34, v36
	v_fmac_f32_e32 v37, v44, v44
	v_add_f32_e32 v34, v37, v34
	v_add_f32_e32 v34, v46, v34
	ds_bpermute_b32 v35, v122, v34
	global_store_dwordx4 v[60:61], v[38:41], off offset:512
	global_store_dwordx4 v[60:61], v[42:45], off offset:528
	v_cvt_pk_bf16_f32 v36, v38, v39
	v_cvt_pk_bf16_f32 v37, v40, v41
	s_waitcnt lgkmcnt(0)
	v_add_f32_e32 v34, v34, v35
	ds_bpermute_b32 v35, v116, v34
	v_cvt_pk_bf16_f32 v38, v42, v43
	v_cvt_pk_bf16_f32 v39, v44, v45
	global_store_dwordx4 v[64:65], v[36:39], off offset:256
	s_and_saveexec_b64 s[2:3], s[42:43]
	s_cbranch_execz .LBB0_1762
	s_waitcnt lgkmcnt(0)
	v_add_f32_e32 v36, v34, v35
	s_lshl_b32 s26, s4, 2
	v_lshlrev_b64 v[34:35], 7, v[50:51]
	s_ashr_i32 s27, s26, 31
	v_lshl_add_u64 v[34:35], s[10:11], 0, v[34:35]
	v_lshl_add_u64 v[34:35], s[26:27], 2, v[34:35]
	v_readlane_b32 s26, v254, 53
	v_readlane_b32 s27, v254, 54
	s_mov_b32 s15, s27
	s_lshl_b32 s26, s46, 2
	v_writelane_b32 v254, s14, 53
	v_lshl_add_u64 v[34:35], v[34:35], 0, s[26:27]
	global_store_dword v[34:35], v36, off
	v_writelane_b32 v254, s15, 54
; __device__ __forceinline__ unsigned cvt_pk_bf16(float lo, float hi) { unsigned r; asm volatile("v_cvt_pk_bf16_f32 %0, %1, %2" : "=v"(r) : "v"(lo), "v"(hi)); return r; }
;     __device__ __forceinline__ void operator()(f32x4 (&acc)[2][2][4][2], const Unit& u, int wr, int wc, int fr, int fq) const {
;         const int row0 = u.pm * BM + wr * 64 + fr; const int col0 = u.pn * BM + wc * 32 + 8 * fq;
; #pragma unroll
;         for (int ai = 0; ai < 2; ++ai)
; #pragma unroll
;             for (int m = 0; m < 4; ++m) { const int row = row0 + ai * HALF + m * 16; float* rowp = X + (size_t)row * ldc + col0; const float* rowi = Xi + (size_t)row * ldc + col0; bf16_t* rowb = XB + (size_t)row * ldc + col0;
;                 float sq = 0.f;
; #pragma unroll
;                 for (int bj = 0; bj < 2; ++bj) { f32x4* p = (f32x4*)(rowp + bj * HALF); const f32x4* pi = (const f32x4*)(rowi + bj * HALF); const f32x4 x0 = pi[0] + acc[ai][bj][m][0], x1 = pi[1] + acc[ai][bj][m][1];
;                     p[0] = x0; p[1] = x1;
;                     u32x4 w; w.x = cvt_pk_bf16(x0[0], x0[1]); w.y = cvt_pk_bf16(x0[2], x0[3]); w.z = cvt_pk_bf16(x1[0], x1[1]); w.w = cvt_pk_bf16(x1[2], x1[3]);
;                     *(u32x4*)(rowb + bj * HALF) = w;
;                     sq += (x0[0] * x0[0] + x0[1] * x0[1]) + (x0[2] * x0[2] + x0[3] * x0[3]) + (x1[0] * x1[0] + x1[1] * x1[1]) + (x1[2] * x1[2] + x1[3] * x1[3]); }
;                 sq += __shfl_xor(sq, 16); sq += __shfl_xor(sq, 32);
;                 if (fq == 0) ss[(size_t)row * 32 + u.pn * 4 + wc] = sq; }
;     }
.LBB0_1762:
	s_or_b64 exec, exec, s[2:3]
	v_add_u32_e32 v34, 0xa0, v158
	s_waitcnt lgkmcnt(0)
	v_ashrrev_i32_e32 v35, 31, v34
	v_lshlrev_b64 v[44:45], 13, v[34:35]
	v_lshl_add_u64 v[36:37], s[0:1], 0, v[44:45]
	v_lshl_add_u64 v[46:47], v[36:37], 0, v[156:157]
	s_nop 1
	v_readlane_b32 s2, v254, 57
	v_lshlrev_b64 v[48:49], 12, v[34:35]
	v_readlane_b32 s3, v254, 58
	v_lshl_add_u64 v[44:45], s[8:9], 0, v[44:45]
	v_lshl_add_u64 v[44:45], v[44:45], 0, v[156:157]
	v_lshl_add_u64 v[48:49], s[2:3], 0, v[48:49]
	v_lshl_add_u64 v[48:49], v[154:155], 1, v[48:49]
	s_waitcnt vmcnt(24)
	s_nop 1
	v_mov_b64_e32 v[36:37], v[176:177]
	v_mov_b64_e32 v[38:39], v[178:179]
	v_mov_b64_e32 v[40:41], v[180:181]
	v_mov_b64_e32 v[42:43], v[182:183]
	v_pk_add_f32 v[32:33], v[32:33], v[38:39]
	v_pk_add_f32 v[30:31], v[30:31], v[36:37]
	v_pk_add_f32 v[28:29], v[28:29], v[42:43]
	v_pk_add_f32 v[26:27], v[26:27], v[40:41]
	global_store_dwordx4 v[44:45], v[30:33], off
	global_store_dwordx4 v[44:45], v[26:29], off offset:16
	v_cvt_pk_bf16_f32 v36, v30, v31
	v_cvt_pk_bf16_f32 v37, v32, v33
	v_cvt_pk_bf16_f32 v38, v26, v27
	v_cvt_pk_bf16_f32 v39, v28, v29
	global_store_dwordx4 v[48:49], v[36:39], off
	s_nop 1
	v_mul_f32_e32 v31, v31, v31
	v_mul_f32_e32 v33, v33, v33
	v_mul_f32_e32 v27, v27, v27
	v_fmac_f32_e32 v31, v30, v30
	v_fmac_f32_e32 v33, v32, v32
	v_mul_f32_e32 v29, v29, v29
	v_fmac_f32_e32 v27, v26, v26
	v_add_f32_e32 v26, v31, v33
	v_fmac_f32_e32 v29, v28, v28
	v_add_f32_e32 v26, v26, v27
	v_add_f32_e32 v30, v29, v26
	s_waitcnt vmcnt(25)
	s_nop 1
	v_mov_b64_e32 v[36:37], v[184:185]
	v_mov_b64_e32 v[38:39], v[186:187]
	v_mov_b64_e32 v[40:41], v[188:189]
	v_mov_b64_e32 v[42:43], v[190:191]
	v_pk_add_f32 v[24:25], v[24:25], v[38:39]
	v_pk_add_f32 v[22:23], v[22:23], v[36:37]
	v_pk_add_f32 v[26:27], v[18:19], v[40:41]
	v_mul_f32_e32 v18, v23, v23
	v_mul_f32_e32 v19, v25, v25
	v_pk_add_f32 v[28:29], v[20:21], v[42:43]
	v_mul_f32_e32 v20, v27, v27
	v_fmac_f32_e32 v18, v22, v22
	v_fmac_f32_e32 v19, v24, v24
	v_mul_f32_e32 v21, v29, v29
	v_fmac_f32_e32 v20, v26, v26
	v_add_f32_e32 v18, v18, v19
	v_add_f32_e32 v18, v18, v20
	v_fmac_f32_e32 v21, v28, v28
	v_add_f32_e32 v18, v21, v18
	v_add_f32_e32 v18, v30, v18
	ds_bpermute_b32 v19, v122, v18
	global_store_dwordx4 v[44:45], v[22:25], off offset:512
	global_store_dwordx4 v[44:45], v[26:29], off offset:528
	v_cvt_pk_bf16_f32 v20, v22, v23
	v_cvt_pk_bf16_f32 v21, v24, v25
	s_waitcnt lgkmcnt(0)
	v_add_f32_e32 v18, v18, v19
	ds_bpermute_b32 v19, v116, v18
	v_cvt_pk_bf16_f32 v22, v26, v27
	v_cvt_pk_bf16_f32 v23, v28, v29
	global_store_dwordx4 v[48:49], v[20:23], off offset:256
	s_and_saveexec_b64 s[2:3], s[42:43]
	s_cbranch_execz .LBB0_1764
	s_waitcnt lgkmcnt(0)
	v_add_f32_e32 v20, v18, v19
	s_lshl_b32 s26, s4, 2
	v_lshlrev_b64 v[18:19], 7, v[34:35]
	s_ashr_i32 s27, s26, 31
	v_lshl_add_u64 v[18:19], s[10:11], 0, v[18:19]
	v_lshl_add_u64 v[18:19], s[26:27], 2, v[18:19]
	v_readlane_b32 s26, v254, 53
	v_readlane_b32 s27, v254, 54
	s_mov_b32 s15, s27
	s_lshl_b32 s26, s46, 2
	v_writelane_b32 v254, s14, 53
	v_lshl_add_u64 v[18:19], v[18:19], 0, s[26:27]
	global_store_dword v[18:19], v20, off
	v_writelane_b32 v254, s15, 54
.LBB0_1764:
	s_or_b64 exec, exec, s[2:3]
	v_add_u32_e32 v18, 0xb0, v158
	s_waitcnt lgkmcnt(0)
	v_ashrrev_i32_e32 v19, 31, v18
	v_lshlrev_b64 v[20:21], 13, v[18:19]
	v_lshl_add_u64 v[22:23], s[8:9], 0, v[20:21]
	v_lshl_add_u64 v[20:21], s[0:1], 0, v[20:21]
	v_readlane_b32 s2, v254, 57
	v_lshl_add_u64 v[30:31], v[20:21], 0, v[156:157]
	v_lshlrev_b64 v[20:21], 12, v[18:19]
	v_readlane_b32 s3, v254, 58
	v_lshl_add_u64 v[28:29], v[22:23], 0, v[156:157]
	s_nop 0
	v_lshl_add_u64 v[20:21], s[2:3], 0, v[20:21]
	v_lshl_add_u64 v[32:33], v[154:155], 1, v[20:21]
	s_nop 1
	s_waitcnt vmcnt(20)
	s_nop 1
	v_mov_b64_e32 v[24:25], v[192:193]
	v_mov_b64_e32 v[26:27], v[194:195]
	v_mov_b64_e32 v[20:21], v[196:197]
	v_mov_b64_e32 v[22:23], v[198:199]
	v_pk_add_f32 v[12:13], v[12:13], v[22:23]
	v_pk_add_f32 v[16:17], v[16:17], v[26:27]
	v_pk_add_f32 v[14:15], v[14:15], v[24:25]
	v_pk_add_f32 v[10:11], v[10:11], v[20:21]
	global_store_dwordx4 v[28:29], v[14:17], off
	global_store_dwordx4 v[28:29], v[10:13], off offset:16
	v_cvt_pk_bf16_f32 v20, v14, v15
	v_cvt_pk_bf16_f32 v21, v16, v17
	v_cvt_pk_bf16_f32 v22, v10, v11
	v_cvt_pk_bf16_f32 v23, v12, v13
	s_nop 0
	v_mul_f32_e32 v15, v15, v15
	v_fmac_f32_e32 v15, v14, v14
	v_mul_f32_e32 v14, v17, v17
	v_fmac_f32_e32 v14, v16, v16
	v_mul_f32_e32 v11, v11, v11
	v_add_f32_e32 v14, v15, v14
	v_fmac_f32_e32 v11, v10, v10
	v_add_f32_e32 v10, v14, v11
	v_mul_f32_e32 v11, v13, v13
	global_store_dwordx4 v[32:33], v[20:23], off
	v_fmac_f32_e32 v11, v12, v12
	s_nop 0
	v_add_f32_e32 v20, v11, v10
	s_nop 1
	s_waitcnt vmcnt(21)
	s_nop 1
	v_mov_b64_e32 v[14:15], v[200:201]
	v_mov_b64_e32 v[16:17], v[202:203]
	v_mov_b64_e32 v[10:11], v[204:205]
	v_mov_b64_e32 v[12:13], v[206:207]
	v_pk_add_f32 v[4:5], v[4:5], v[12:13]
	v_pk_add_f32 v[8:9], v[8:9], v[16:17]
	v_pk_add_f32 v[6:7], v[6:7], v[14:15]
	v_pk_add_f32 v[2:3], v[2:3], v[10:11]
	global_store_dwordx4 v[28:29], v[6:9], off offset:512
	global_store_dwordx4 v[28:29], v[2:5], off offset:528
	v_cvt_pk_bf16_f32 v10, v6, v7
	v_cvt_pk_bf16_f32 v11, v8, v9
	v_cvt_pk_bf16_f32 v12, v2, v3
	v_cvt_pk_bf16_f32 v13, v4, v5
	s_nop 0
	v_mul_f32_e32 v7, v7, v7
	v_fmac_f32_e32 v7, v6, v6
	v_mul_f32_e32 v6, v9, v9
	v_fmac_f32_e32 v6, v8, v8
	v_mul_f32_e32 v3, v3, v3
	v_add_f32_e32 v6, v7, v6
	v_fmac_f32_e32 v3, v2, v2
	v_add_f32_e32 v2, v6, v3
	v_mul_f32_e32 v3, v5, v5
	v_fmac_f32_e32 v3, v4, v4
	v_add_f32_e32 v2, v3, v2
	v_add_f32_e32 v2, v20, v2
	ds_bpermute_b32 v3, v122, v2
	global_store_dwordx4 v[32:33], v[10:13], off offset:256
	s_waitcnt lgkmcnt(0)
	v_add_f32_e32 v2, v2, v3
	ds_bpermute_b32 v3, v116, v2
	s_and_saveexec_b64 s[2:3], s[42:43]
	s_cbranch_execz .LBB0_1766
	s_waitcnt lgkmcnt(0)
	v_add_f32_e32 v4, v2, v3
	s_lshl_b32 s26, s4, 2
	v_lshlrev_b64 v[2:3], 7, v[18:19]
	s_ashr_i32 s27, s26, 31
	v_lshl_add_u64 v[2:3], s[10:11], 0, v[2:3]
	v_lshl_add_u64 v[2:3], s[26:27], 2, v[2:3]
	v_readlane_b32 s26, v254, 53
	v_readlane_b32 s27, v254, 54
	s_mov_b32 s15, s27
	s_lshl_b32 s26, s46, 2
	v_writelane_b32 v254, s14, 53
	v_lshl_add_u64 v[2:3], v[2:3], 0, s[26:27]
	global_store_dword v[2:3], v4, off
	v_writelane_b32 v254, s15, 54

; #define LAS __attribute__((address_space(3)))
; __device__ __forceinline__ void cv_pair(const PT& a, LAS unsigned char* lds, int l, int r, int wave, int lane) {
;     LAS float* s0 = (LAS float*)(lds + wave * CV_WAVE_B); LAS float* s1 = (LAS float*)(lds + wave * CV_WAVE_B + CV_TILE_B);
;     const bool two = r + 1 < IT_LAYER;
;     const CvItem i0 = cv_decode(a, l, r), i1 = cv_decode(a, l, two ? r + 1 : r);
;     f32x4 v0[8], v1[8]; float g0[8], g1[8];
;     cv_load(i0, lane, v0, g0); cv_load(i1, lane, v1, g1);
;     cv_lds_write(s0, lane, v0, g0); cv_lds_write(s1, lane, v1, g1);
;     for (int it = 0; it < budget; ++it) {
;         unsigned r = 0; if (lane == 0) r = __hip_atomic_fetch_add(ctr, 2u, __ATOMIC_RELAXED, __HIP_MEMORY_SCOPE_AGENT);
;         r = (unsigned)__builtin_amdgcn_readfirstlane((int)r) + (unsigned)CV_PRO_ITEMS;
;         if (r >= (unsigned)IT_LAYER) break;
;         cv_pair(a, lds, l, (int)r, wave, lane);
;     }
; }
.LBB0_1843:
	v_readlane_b32 s2, v252, 0
	s_cmp_lt_u32 s2, 128
	s_cbranch_scc1 .LcvqB_skip
	s_cmp_gt_u32 s36, 2
	s_cbranch_scc1 .LcvqB_skip
	v_writelane_b32 v255, s0, 8
	v_writelane_b32 v255, s1, 9
	v_writelane_b32 v255, s40, 10
	v_writelane_b32 v255, s41, 11
	s_mov_b32 s64, s36
	v_readlane_b32 s0, v254, 53
	v_readlane_b32 s1, v254, 54
	s_mov_b32 s3, s1
	s_lshl_b32 s2, s36, 6
	s_lshl_b64 s[0:1], s[2:3], 2
	v_readlane_b32 s4, v254, 60
	v_readlane_b32 s5, v254, 61
	s_add_u32 s0, s4, s0
	s_addc_u32 s1, s5, s1
	s_add_u32 s0, s0, 0x8000
	s_addc_u32 s1, s1, 0
	s_add_i32 s2, s36, 1
	s_mul_hi_u32 s33, s2, 0x2c00000
	s_mul_i32 s34, s2, 0x2c00000
	s_mul_hi_u32 s35, s2, 0x1600000
	s_mul_i32 s50, s2, 0x1600000
	s_lshl_b32 s6, s2, 11
	s_mov_b32 s7, s3
	s_lshl_b64 s[8:9], s[2:3], 24
	s_lshl_b64 s[10:11], s[2:3], 23
	s_mul_hi_u32 s51, s2, 0xc00000
	s_mul_i32 s52, s2, 0xc00000
	s_mul_hi_u32 s53, s2, 0x7280000
	s_mul_i32 s54, s2, 0x7280000
	s_mul_hi_u32 s55, s2, 0x3a00000
	v_writelane_b32 v254, s2, 53
	v_mov_b32_e32 v2, v0
	s_mul_i32 s56, s2, 0x3a00000
	v_writelane_b32 v254, s3, 54
	s_waitcnt vmcnt(0) lgkmcnt(0)
	s_barrier
	s_movk_i32 s2, 0x4200
	v_lshrrev_b32_e32 v1, 6, v2
	v_and_b32_e32 v3, 63, v2
	v_readfirstlane_b32 s100, v1
	v_readlane_b32 s101, v252, 0
	s_sub_u32 s101, s101, 128
	s_lshl_b32 s101, s101, 3
	s_add_u32 s100, s100, s101
	s_lshl_b32 s100, s100, 1
	s_add_u32 s100, s100, 0x2000
	v_mul_lo_u32 v1, v1, s2
	v_cmp_eq_u32_e64 s[40:41], 0, v3
	v_add_u32_e32 v3, 0, v1
	v_lshlrev_b32_e32 v1, 2, v2
	v_and_b32_e32 v66, 28, v1
	v_bfe_u32 v1, v2, 3, 3
	v_lshlrev_b32_e32 v2, 3, v2
	v_and_b32_e32 v68, 56, v2
	v_lshl_add_u32 v4, v66, 2, v3
	v_mul_u32_u24_e32 v5, 0x84, v1
	v_mul_u32_u24_e32 v2, 0x84, v68
	v_lshlrev_b32_e32 v6, 2, v1
	v_or_b32_e32 v67, 8, v1
	v_or_b32_e32 v69, 16, v1
	v_or_b32_e32 v71, 24, v1
	v_or_b32_e32 v73, 32, v1
	v_or_b32_e32 v75, 40, v1
	v_or_b32_e32 v77, 48, v1
	v_or_b32_e32 v79, 56, v1
	v_add3_u32 v81, v3, v2, v6
	s_mov_b32 s57, 0x1
	v_add_u32_e32 v83, v4, v5
	s_branch .LcvqB_1381

; __device__ __forceinline__ unsigned cvt_pk_bf16(float lo, float hi) { unsigned r; asm volatile("v_cvt_pk_bf16_f32 %0, %1, %2" : "=v"(r) : "v"(lo), "v"(hi)); return r; }
;     __device__ __forceinline__ void operator()(f32x4 (&acc)[2][2][4][2], const Unit& u, int wr, int wc, int fr, int fq) const {
;         const int row0 = u.pm * BM + wr * 64 + fr; const int col0 = u.pn * BM + wc * 32 + 8 * fq;
; #pragma unroll
;         for (int ai = 0; ai < 2; ++ai)
; #pragma unroll
;             for (int m = 0; m < 4; ++m) { const int row = row0 + ai * HALF + m * 16; float* rowp = X + (size_t)row * ldc + col0; const float* rowi = Xi + (size_t)row * ldc + col0; bf16_t* rowb = XB + (size_t)row * ldc + col0;
;                 float sq = 0.f;
; #pragma unroll
;                 for (int bj = 0; bj < 2; ++bj) { f32x4* p = (f32x4*)(rowp + bj * HALF); const f32x4* pi = (const f32x4*)(rowi + bj * HALF); const f32x4 x0 = pi[0] + acc[ai][bj][m][0], x1 = pi[1] + acc[ai][bj][m][1];
;                     p[0] = x0; p[1] = x1;
;                     u32x4 w; w.x = cvt_pk_bf16(x0[0], x0[1]); w.y = cvt_pk_bf16(x0[2], x0[3]); w.z = cvt_pk_bf16(x1[0], x1[1]); w.w = cvt_pk_bf16(x1[2], x1[3]);
;                     *(u32x4*)(rowb + bj * HALF) = w;
;                     sq += (x0[0] * x0[0] + x0[1] * x0[1]) + (x0[2] * x0[2] + x0[3] * x0[3]) + (x1[0] * x1[0] + x1[1] * x1[1]) + (x1[2] * x1[2] + x1[3] * x1[3]); }
;                 sq += __shfl_xor(sq, 16); sq += __shfl_xor(sq, 32);
;                 if (fq == 0) ss[(size_t)row * 32 + u.pn * 4 + wc] = sq; }
;     }
.LBB0_1920:
	v_lshl_add_u32 v158, s47, 8, v1
	v_lshl_or_b32 v154, s30, 8, v161
	v_ashrrev_i32_e32 v159, 31, v158
	v_ashrrev_i32_e32 v155, 31, v154
	v_lshlrev_b64 v[130:131], 13, v[158:159]
	v_lshlrev_b64 v[156:157], 2, v[154:155]
	v_lshl_add_u64 v[134:135], s[8:9], 0, v[130:131]
	v_lshl_add_u64 v[134:135], v[134:135], 0, v[156:157]
	v_mov_b64_e32 v[248:249], v[134:135]
	global_load_dwordx4 v[176:179], v[248:249], off
	global_load_dwordx4 v[180:183], v[248:249], off offset:16
	global_load_dwordx4 v[184:187], v[248:249], off offset:512
	global_load_dwordx4 v[188:191], v[248:249], off offset:528
	s_mov_b64 s[100:101], 0x20000
	v_lshl_add_u64 v[250:251], v[248:249], 0, s[100:101]
	global_load_dwordx4 v[192:195], v[250:251], off
	global_load_dwordx4 v[196:199], v[250:251], off offset:16
	global_load_dwordx4 v[200:203], v[250:251], off offset:512
	global_load_dwordx4 v[204:207], v[250:251], off offset:528
	s_mov_b64 s[100:101], 0x40000
	v_lshl_add_u64 v[250:251], v[248:249], 0, s[100:101]
	global_load_dwordx4 v[232:235], v[250:251], off
	global_load_dwordx4 v[236:239], v[250:251], off offset:16
	global_load_dwordx4 v[240:243], v[250:251], off offset:512
	global_load_dwordx4 v[244:247], v[250:251], off offset:528
	s_nop 1
	v_readlane_b32 s2, v254, 57
	v_lshlrev_b64 v[140:141], 12, v[158:159]
	v_readlane_b32 s3, v254, 58
	v_lshl_add_u64 v[130:131], s[0:1], 0, v[130:131]
	v_lshl_add_u64 v[130:131], v[130:131], 0, v[156:157]
	v_lshl_add_u64 v[140:141], s[2:3], 0, v[140:141]
	v_lshl_add_u64 v[140:141], v[154:155], 1, v[140:141]
	s_waitcnt vmcnt(10)
	s_nop 1
	v_mov_b64_e32 v[164:165], v[176:177]
	v_mov_b64_e32 v[166:167], v[178:179]
	v_mov_b64_e32 v[168:169], v[180:181]
	v_mov_b64_e32 v[170:171], v[182:183]
	v_pk_add_f32 v[128:129], v[128:129], v[166:167]
	v_pk_add_f32 v[126:127], v[126:127], v[164:165]
	v_pk_add_f32 v[166:167], v[124:125], v[170:171]
	v_pk_add_f32 v[164:165], v[122:123], v[168:169]
	global_store_dwordx4 v[130:131], v[126:129], off
	global_store_dwordx4 v[130:131], v[164:167], off offset:16
	v_cvt_pk_bf16_f32 v122, v126, v127
	v_cvt_pk_bf16_f32 v123, v128, v129
	v_cvt_pk_bf16_f32 v124, v164, v165
	v_cvt_pk_bf16_f32 v125, v166, v167
	global_store_dwordx4 v[140:141], v[122:125], off
	s_nop 1
	v_mul_f32_e32 v124, v127, v127
	v_mul_f32_e32 v125, v129, v129
	v_mul_f32_e32 v127, v165, v165
	v_fmac_f32_e32 v124, v126, v126
	v_fmac_f32_e32 v125, v128, v128
	v_mul_f32_e32 v129, v167, v167
	v_fmac_f32_e32 v127, v164, v164
	v_add_f32_e32 v124, v124, v125
	v_fmac_f32_e32 v129, v166, v166
	v_add_f32_e32 v124, v124, v127
	v_add_f32_e32 v128, v129, v124
	v_and_b32_e32 v123, 64, v223
	v_xor_b32_e32 v122, 16, v223
	v_add_u32_e32 v123, 64, v123
	v_cmp_lt_i32_e32 vcc, v122, v123
	v_xor_b32_e32 v134, 32, v223
	s_waitcnt vmcnt(11)
	s_nop 1
	v_mov_b64_e32 v[168:169], v[184:185]
	v_mov_b64_e32 v[170:171], v[186:187]
	v_mov_b64_e32 v[172:173], v[188:189]
	v_mov_b64_e32 v[174:175], v[190:191]
	s_mov_b64 s[100:101], 0x60000
	v_lshl_add_u64 v[250:251], v[248:249], 0, s[100:101]
	global_load_dwordx4 v[176:179], v[250:251], off
	global_load_dwordx4 v[180:183], v[250:251], off offset:16
	global_load_dwordx4 v[184:187], v[250:251], off offset:512
	global_load_dwordx4 v[188:191], v[250:251], off offset:528
	v_pk_add_f32 v[120:121], v[120:121], v[170:171]
	v_pk_add_f32 v[118:119], v[118:119], v[168:169]
	v_pk_add_f32 v[124:125], v[114:115], v[172:173]
	v_mul_f32_e32 v114, v119, v119
	v_mul_f32_e32 v115, v121, v121
	v_pk_add_f32 v[126:127], v[116:117], v[174:175]
	v_mul_f32_e32 v116, v125, v125
	v_fmac_f32_e32 v114, v118, v118
	v_fmac_f32_e32 v115, v120, v120
	v_mul_f32_e32 v117, v127, v127
	v_fmac_f32_e32 v116, v124, v124
	v_add_f32_e32 v114, v114, v115
	v_fmac_f32_e32 v117, v126, v126
	v_add_f32_e32 v114, v114, v116
	v_cndmask_b32_e32 v122, v223, v122, vcc
	v_add_f32_e32 v114, v117, v114
	v_lshlrev_b32_e32 v122, 2, v122
	v_add_f32_e32 v114, v128, v114
	ds_bpermute_b32 v115, v122, v114
	v_cmp_lt_i32_e32 vcc, v134, v123
	global_store_dwordx4 v[130:131], v[118:121], off offset:512
	global_store_dwordx4 v[130:131], v[124:127], off offset:528
	v_cndmask_b32_e32 v116, v223, v134, vcc
	v_lshlrev_b32_e32 v116, 2, v116
	s_waitcnt lgkmcnt(0)
	v_add_f32_e32 v114, v114, v115
	ds_bpermute_b32 v115, v116, v114
	v_cvt_pk_bf16_f32 v118, v118, v119
	v_cvt_pk_bf16_f32 v119, v120, v121
	v_cvt_pk_bf16_f32 v120, v124, v125
	v_cvt_pk_bf16_f32 v121, v126, v127
	global_store_dwordx4 v[140:141], v[118:121], off offset:256
	s_and_saveexec_b64 s[2:3], s[40:41]
	s_cbranch_execz .LBB0_1922
	s_waitcnt lgkmcnt(0)
	v_add_f32_e32 v117, v114, v115
	s_lshl_b32 s16, s30, 2
	v_lshlrev_b64 v[114:115], 7, v[158:159]
	s_ashr_i32 s17, s16, 31
	v_lshl_add_u64 v[114:115], s[10:11], 0, v[114:115]
	v_lshl_add_u64 v[114:115], s[16:17], 2, v[114:115]
	v_readlane_b32 s16, v254, 53
	v_readlane_b32 s17, v254, 54
	s_mov_b32 s19, s17
	s_lshl_b32 s18, s37, 2
	v_writelane_b32 v254, s16, 53
	v_lshl_add_u64 v[114:115], v[114:115], 0, s[18:19]
	global_store_dword v[114:115], v117, off
	v_writelane_b32 v254, s17, 54
; __device__ __forceinline__ unsigned cvt_pk_bf16(float lo, float hi) { unsigned r; asm volatile("v_cvt_pk_bf16_f32 %0, %1, %2" : "=v"(r) : "v"(lo), "v"(hi)); return r; }
;     __device__ __forceinline__ void operator()(f32x4 (&acc)[2][2][4][2], const Unit& u, int wr, int wc, int fr, int fq) const {
;         const int row0 = u.pm * BM + wr * 64 + fr; const int col0 = u.pn * BM + wc * 32 + 8 * fq;
; #pragma unroll
;         for (int ai = 0; ai < 2; ++ai)
; #pragma unroll
;             for (int m = 0; m < 4; ++m) { const int row = row0 + ai * HALF + m * 16; float* rowp = X + (size_t)row * ldc + col0; const float* rowi = Xi + (size_t)row * ldc + col0; bf16_t* rowb = XB + (size_t)row * ldc + col0;
;                 float sq = 0.f;
; #pragma unroll
;                 for (int bj = 0; bj < 2; ++bj) { f32x4* p = (f32x4*)(rowp + bj * HALF); const f32x4* pi = (const f32x4*)(rowi + bj * HALF); const f32x4 x0 = pi[0] + acc[ai][bj][m][0], x1 = pi[1] + acc[ai][bj][m][1];
;                     p[0] = x0; p[1] = x1;
;                     u32x4 w; w.x = cvt_pk_bf16(x0[0], x0[1]); w.y = cvt_pk_bf16(x0[2], x0[3]); w.z = cvt_pk_bf16(x1[0], x1[1]); w.w = cvt_pk_bf16(x1[2], x1[3]);
;                     *(u32x4*)(rowb + bj * HALF) = w;
;                     sq += (x0[0] * x0[0] + x0[1] * x0[1]) + (x0[2] * x0[2] + x0[3] * x0[3]) + (x1[0] * x1[0] + x1[1] * x1[1]) + (x1[2] * x1[2] + x1[3] * x1[3]); }
;                 sq += __shfl_xor(sq, 16); sq += __shfl_xor(sq, 32);
;                 if (fq == 0) ss[(size_t)row * 32 + u.pn * 4 + wc] = sq; }
;     }
.LBB0_1922:
	s_or_b64 exec, exec, s[2:3]
	v_or_b32_e32 v114, 16, v158
	s_waitcnt lgkmcnt(0)
	v_ashrrev_i32_e32 v115, 31, v114
	v_lshlrev_b64 v[128:129], 13, v[114:115]
	v_lshl_add_u64 v[118:119], s[8:9], 0, v[128:129]
	v_lshl_add_u64 v[130:131], v[118:119], 0, v[156:157]
	s_nop 1
	v_readlane_b32 s2, v254, 57
	v_lshlrev_b64 v[134:135], 12, v[114:115]
	v_readlane_b32 s3, v254, 58
	v_lshl_add_u64 v[128:129], s[0:1], 0, v[128:129]
	v_lshl_add_u64 v[128:129], v[128:129], 0, v[156:157]
	v_lshl_add_u64 v[134:135], s[2:3], 0, v[134:135]
	v_lshl_add_u64 v[134:135], v[154:155], 1, v[134:135]
	s_waitcnt vmcnt(17)
	s_nop 1
	v_mov_b64_e32 v[118:119], v[192:193]
	v_mov_b64_e32 v[120:121], v[194:195]
	v_mov_b64_e32 v[124:125], v[196:197]
	v_mov_b64_e32 v[126:127], v[198:199]
	v_pk_add_f32 v[112:113], v[112:113], v[120:121]
	v_pk_add_f32 v[110:111], v[110:111], v[118:119]
	v_pk_add_f32 v[108:109], v[108:109], v[126:127]
	v_pk_add_f32 v[106:107], v[106:107], v[124:125]
	global_store_dwordx4 v[128:129], v[110:113], off
	global_store_dwordx4 v[128:129], v[106:109], off offset:16
	v_cvt_pk_bf16_f32 v118, v110, v111
	v_cvt_pk_bf16_f32 v119, v112, v113
	v_cvt_pk_bf16_f32 v120, v106, v107
	v_cvt_pk_bf16_f32 v121, v108, v109
	global_store_dwordx4 v[134:135], v[118:121], off
	s_nop 1
	v_mul_f32_e32 v111, v111, v111
	v_mul_f32_e32 v113, v113, v113
	v_mul_f32_e32 v107, v107, v107
	v_fmac_f32_e32 v111, v110, v110
	v_fmac_f32_e32 v113, v112, v112
	v_mul_f32_e32 v109, v109, v109
	v_fmac_f32_e32 v107, v106, v106
	v_add_f32_e32 v106, v111, v113
	v_fmac_f32_e32 v109, v108, v108
	v_add_f32_e32 v106, v106, v107
	v_add_f32_e32 v110, v109, v106
	s_waitcnt vmcnt(18)
	s_nop 1
	v_mov_b64_e32 v[118:119], v[200:201]
	v_mov_b64_e32 v[120:121], v[202:203]
	v_mov_b64_e32 v[124:125], v[204:205]
	v_mov_b64_e32 v[126:127], v[206:207]
	s_mov_b64 s[100:101], 0x100000
	v_lshl_add_u64 v[250:251], v[248:249], 0, s[100:101]
	global_load_dwordx4 v[192:195], v[250:251], off
	global_load_dwordx4 v[196:199], v[250:251], off offset:16
	global_load_dwordx4 v[200:203], v[250:251], off offset:512
	global_load_dwordx4 v[204:207], v[250:251], off offset:528
	v_pk_add_f32 v[104:105], v[104:105], v[120:121]
	v_pk_add_f32 v[102:103], v[102:103], v[118:119]
	v_pk_add_f32 v[106:107], v[98:99], v[124:125]
	v_mul_f32_e32 v98, v103, v103
	v_mul_f32_e32 v99, v105, v105
	v_pk_add_f32 v[108:109], v[100:101], v[126:127]
	v_mul_f32_e32 v100, v107, v107
	v_fmac_f32_e32 v98, v102, v102
	v_fmac_f32_e32 v99, v104, v104
	v_mul_f32_e32 v101, v109, v109
	v_fmac_f32_e32 v100, v106, v106
	v_add_f32_e32 v98, v98, v99
	v_add_f32_e32 v98, v98, v100
	v_fmac_f32_e32 v101, v108, v108
	v_add_f32_e32 v98, v101, v98
	v_add_f32_e32 v98, v110, v98
	ds_bpermute_b32 v99, v122, v98
	global_store_dwordx4 v[128:129], v[102:105], off offset:512
	global_store_dwordx4 v[128:129], v[106:109], off offset:528
	v_cvt_pk_bf16_f32 v100, v102, v103
	v_cvt_pk_bf16_f32 v101, v104, v105
	s_waitcnt lgkmcnt(0)
	v_add_f32_e32 v98, v98, v99
	ds_bpermute_b32 v99, v116, v98
	v_cvt_pk_bf16_f32 v102, v106, v107
	v_cvt_pk_bf16_f32 v103, v108, v109
	global_store_dwordx4 v[134:135], v[100:103], off offset:256
	s_and_saveexec_b64 s[2:3], s[40:41]
	s_cbranch_execz .LBB0_1924
	s_waitcnt lgkmcnt(0)
	v_add_f32_e32 v100, v98, v99
	s_lshl_b32 s16, s30, 2
	v_lshlrev_b64 v[98:99], 7, v[114:115]
	s_ashr_i32 s17, s16, 31
	v_lshl_add_u64 v[98:99], s[10:11], 0, v[98:99]
	v_lshl_add_u64 v[98:99], s[16:17], 2, v[98:99]
	v_readlane_b32 s16, v254, 53
	v_readlane_b32 s17, v254, 54
	s_mov_b32 s19, s17
	s_lshl_b32 s18, s37, 2
	v_writelane_b32 v254, s16, 53
	v_lshl_add_u64 v[98:99], v[98:99], 0, s[18:19]
	global_store_dword v[98:99], v100, off
	v_writelane_b32 v254, s17, 54
.LBB0_1924:
	s_or_b64 exec, exec, s[2:3]
	v_or_b32_e32 v98, 32, v158
	s_waitcnt lgkmcnt(0)
	v_ashrrev_i32_e32 v99, 31, v98
	v_lshlrev_b64 v[108:109], 13, v[98:99]
	v_lshl_add_u64 v[100:101], s[8:9], 0, v[108:109]
	v_lshl_add_u64 v[110:111], v[100:101], 0, v[156:157]
	s_nop 1
	v_readlane_b32 s2, v254, 57
	v_lshlrev_b64 v[112:113], 12, v[98:99]
	v_readlane_b32 s3, v254, 58
	v_lshl_add_u64 v[108:109], s[0:1], 0, v[108:109]
	v_lshl_add_u64 v[108:109], v[108:109], 0, v[156:157]
	v_lshl_add_u64 v[112:113], s[2:3], 0, v[112:113]
	v_lshl_add_u64 v[112:113], v[154:155], 1, v[112:113]
	s_waitcnt vmcnt(24)
	s_nop 1
	v_mov_b64_e32 v[100:101], v[232:233]
	v_mov_b64_e32 v[102:103], v[234:235]
	v_mov_b64_e32 v[104:105], v[236:237]
	v_mov_b64_e32 v[106:107], v[238:239]
	v_pk_add_f32 v[96:97], v[96:97], v[102:103]
	v_pk_add_f32 v[94:95], v[94:95], v[100:101]
	v_pk_add_f32 v[92:93], v[92:93], v[106:107]
	v_pk_add_f32 v[90:91], v[90:91], v[104:105]
	global_store_dwordx4 v[108:109], v[94:97], off
	global_store_dwordx4 v[108:109], v[90:93], off offset:16
	v_cvt_pk_bf16_f32 v100, v94, v95
	v_cvt_pk_bf16_f32 v101, v96, v97
	v_cvt_pk_bf16_f32 v102, v90, v91
	v_cvt_pk_bf16_f32 v103, v92, v93
	global_store_dwordx4 v[112:113], v[100:103], off
	s_nop 1
	v_mul_f32_e32 v95, v95, v95
	v_mul_f32_e32 v97, v97, v97
	v_mul_f32_e32 v91, v91, v91
	v_fmac_f32_e32 v95, v94, v94
	v_fmac_f32_e32 v97, v96, v96
	v_mul_f32_e32 v93, v93, v93
	v_fmac_f32_e32 v91, v90, v90
	v_add_f32_e32 v90, v95, v97
	v_fmac_f32_e32 v93, v92, v92
	v_add_f32_e32 v90, v90, v91
	v_add_f32_e32 v94, v93, v90
	s_waitcnt vmcnt(25)
	s_nop 1
	v_mov_b64_e32 v[100:101], v[240:241]
	v_mov_b64_e32 v[102:103], v[242:243]
	v_mov_b64_e32 v[104:105], v[244:245]
	v_mov_b64_e32 v[106:107], v[246:247]
	s_mov_b64 s[100:101], 0x120000
	v_lshl_add_u64 v[250:251], v[248:249], 0, s[100:101]
	global_load_dwordx4 v[232:235], v[250:251], off
	global_load_dwordx4 v[236:239], v[250:251], off offset:16
	global_load_dwordx4 v[240:243], v[250:251], off offset:512
	global_load_dwordx4 v[244:247], v[250:251], off offset:528
	v_pk_add_f32 v[88:89], v[88:89], v[102:103]
	v_pk_add_f32 v[86:87], v[86:87], v[100:101]
	v_pk_add_f32 v[90:91], v[82:83], v[104:105]
	v_mul_f32_e32 v82, v87, v87
	v_mul_f32_e32 v83, v89, v89
	v_pk_add_f32 v[92:93], v[84:85], v[106:107]
	v_mul_f32_e32 v84, v91, v91
	v_fmac_f32_e32 v82, v86, v86
	v_fmac_f32_e32 v83, v88, v88
	v_mul_f32_e32 v85, v93, v93
	v_fmac_f32_e32 v84, v90, v90
	v_add_f32_e32 v82, v82, v83
	v_add_f32_e32 v82, v82, v84
	v_fmac_f32_e32 v85, v92, v92
	v_add_f32_e32 v82, v85, v82
	v_add_f32_e32 v82, v94, v82
	ds_bpermute_b32 v83, v122, v82
	global_store_dwordx4 v[108:109], v[86:89], off offset:512
	global_store_dwordx4 v[108:109], v[90:93], off offset:528
	v_cvt_pk_bf16_f32 v84, v86, v87
	v_cvt_pk_bf16_f32 v85, v88, v89
	s_waitcnt lgkmcnt(0)
	v_add_f32_e32 v82, v82, v83
	ds_bpermute_b32 v83, v116, v82
	v_cvt_pk_bf16_f32 v86, v90, v91
	v_cvt_pk_bf16_f32 v87, v92, v93
	global_store_dwordx4 v[112:113], v[84:87], off offset:256
	s_and_saveexec_b64 s[2:3], s[40:41]
	s_cbranch_execz .LBB0_1926
; __device__ __forceinline__ unsigned cvt_pk_bf16(float lo, float hi) { unsigned r; asm volatile("v_cvt_pk_bf16_f32 %0, %1, %2" : "=v"(r) : "v"(lo), "v"(hi)); return r; }
;     __device__ __forceinline__ void operator()(f32x4 (&acc)[2][2][4][2], const Unit& u, int wr, int wc, int fr, int fq) const {
;         const int row0 = u.pm * BM + wr * 64 + fr; const int col0 = u.pn * BM + wc * 32 + 8 * fq;
; #pragma unroll
;         for (int ai = 0; ai < 2; ++ai)
; #pragma unroll
;             for (int m = 0; m < 4; ++m) { const int row = row0 + ai * HALF + m * 16; float* rowp = X + (size_t)row * ldc + col0; const float* rowi = Xi + (size_t)row * ldc + col0; bf16_t* rowb = XB + (size_t)row * ldc + col0;
;                 float sq = 0.f;
; #pragma unroll
;                 for (int bj = 0; bj < 2; ++bj) { f32x4* p = (f32x4*)(rowp + bj * HALF); const f32x4* pi = (const f32x4*)(rowi + bj * HALF); const f32x4 x0 = pi[0] + acc[ai][bj][m][0], x1 = pi[1] + acc[ai][bj][m][1];
;                     p[0] = x0; p[1] = x1;
;                     u32x4 w; w.x = cvt_pk_bf16(x0[0], x0[1]); w.y = cvt_pk_bf16(x0[2], x0[3]); w.z = cvt_pk_bf16(x1[0], x1[1]); w.w = cvt_pk_bf16(x1[2], x1[3]);
;                     *(u32x4*)(rowb + bj * HALF) = w;
;                     sq += (x0[0] * x0[0] + x0[1] * x0[1]) + (x0[2] * x0[2] + x0[3] * x0[3]) + (x1[0] * x1[0] + x1[1] * x1[1]) + (x1[2] * x1[2] + x1[3] * x1[3]); }
;                 sq += __shfl_xor(sq, 16); sq += __shfl_xor(sq, 32);
;                 if (fq == 0) ss[(size_t)row * 32 + u.pn * 4 + wc] = sq; }
;     }
	s_waitcnt lgkmcnt(0)
	v_add_f32_e32 v84, v82, v83
	s_lshl_b32 s16, s30, 2
	v_lshlrev_b64 v[82:83], 7, v[98:99]
	s_ashr_i32 s17, s16, 31
	v_lshl_add_u64 v[82:83], s[10:11], 0, v[82:83]
	v_lshl_add_u64 v[82:83], s[16:17], 2, v[82:83]
	v_readlane_b32 s16, v254, 53
	v_readlane_b32 s17, v254, 54
	s_mov_b32 s19, s17
	s_lshl_b32 s18, s37, 2
	v_writelane_b32 v254, s16, 53
	v_lshl_add_u64 v[82:83], v[82:83], 0, s[18:19]
	global_store_dword v[82:83], v84, off
	v_writelane_b32 v254, s17, 54
.LBB0_1926:
	s_or_b64 exec, exec, s[2:3]
	v_or_b32_e32 v82, 48, v158
	s_waitcnt lgkmcnt(0)
	v_ashrrev_i32_e32 v83, 31, v82
	v_lshlrev_b64 v[92:93], 13, v[82:83]
	v_lshl_add_u64 v[84:85], s[8:9], 0, v[92:93]
	v_lshl_add_u64 v[94:95], v[84:85], 0, v[156:157]
	s_nop 1
	v_readlane_b32 s2, v254, 57
	v_lshlrev_b64 v[96:97], 12, v[82:83]
	v_readlane_b32 s3, v254, 58
	v_lshl_add_u64 v[92:93], s[0:1], 0, v[92:93]
	v_lshl_add_u64 v[92:93], v[92:93], 0, v[156:157]
	v_lshl_add_u64 v[96:97], s[2:3], 0, v[96:97]
	v_lshl_add_u64 v[96:97], v[154:155], 1, v[96:97]
	s_waitcnt vmcnt(28)
	s_nop 1
	v_mov_b64_e32 v[84:85], v[176:177]
	v_mov_b64_e32 v[86:87], v[178:179]
	v_mov_b64_e32 v[88:89], v[180:181]
	v_mov_b64_e32 v[90:91], v[182:183]
	v_pk_add_f32 v[80:81], v[80:81], v[86:87]
	v_pk_add_f32 v[78:79], v[78:79], v[84:85]
	v_pk_add_f32 v[76:77], v[76:77], v[90:91]
	v_pk_add_f32 v[74:75], v[74:75], v[88:89]
	global_store_dwordx4 v[92:93], v[78:81], off
	global_store_dwordx4 v[92:93], v[74:77], off offset:16
	v_cvt_pk_bf16_f32 v84, v78, v79
	v_cvt_pk_bf16_f32 v85, v80, v81
	v_cvt_pk_bf16_f32 v86, v74, v75
	v_cvt_pk_bf16_f32 v87, v76, v77
	global_store_dwordx4 v[96:97], v[84:87], off
	s_nop 1
	v_mul_f32_e32 v79, v79, v79
	v_mul_f32_e32 v81, v81, v81
	v_mul_f32_e32 v75, v75, v75
	v_fmac_f32_e32 v79, v78, v78
	v_fmac_f32_e32 v81, v80, v80
	v_mul_f32_e32 v77, v77, v77
	v_fmac_f32_e32 v75, v74, v74
	v_add_f32_e32 v74, v79, v81
	v_fmac_f32_e32 v77, v76, v76
	v_add_f32_e32 v74, v74, v75
	v_add_f32_e32 v78, v77, v74
	s_waitcnt vmcnt(29)
	s_nop 1
	v_mov_b64_e32 v[84:85], v[184:185]
	v_mov_b64_e32 v[86:87], v[186:187]
	v_mov_b64_e32 v[88:89], v[188:189]
	v_mov_b64_e32 v[90:91], v[190:191]
	s_mov_b64 s[100:101], 0x140000
	v_lshl_add_u64 v[250:251], v[248:249], 0, s[100:101]
	global_load_dwordx4 v[176:179], v[250:251], off
	global_load_dwordx4 v[180:183], v[250:251], off offset:16
	global_load_dwordx4 v[184:187], v[250:251], off offset:512
	global_load_dwordx4 v[188:191], v[250:251], off offset:528
	v_pk_add_f32 v[72:73], v[72:73], v[86:87]
	v_pk_add_f32 v[70:71], v[70:71], v[84:85]
	v_pk_add_f32 v[74:75], v[66:67], v[88:89]
	v_mul_f32_e32 v66, v71, v71
	v_mul_f32_e32 v67, v73, v73
	v_pk_add_f32 v[76:77], v[68:69], v[90:91]
	v_mul_f32_e32 v68, v75, v75
	v_fmac_f32_e32 v66, v70, v70
	v_fmac_f32_e32 v67, v72, v72
	v_mul_f32_e32 v69, v77, v77
	v_fmac_f32_e32 v68, v74, v74
	v_add_f32_e32 v66, v66, v67
	v_add_f32_e32 v66, v66, v68
	v_fmac_f32_e32 v69, v76, v76
	v_add_f32_e32 v66, v69, v66
	v_add_f32_e32 v66, v78, v66
	ds_bpermute_b32 v67, v122, v66
	global_store_dwordx4 v[92:93], v[70:73], off offset:512
	global_store_dwordx4 v[92:93], v[74:77], off offset:528
	v_cvt_pk_bf16_f32 v68, v70, v71
	v_cvt_pk_bf16_f32 v69, v72, v73
	s_waitcnt lgkmcnt(0)
	v_add_f32_e32 v66, v66, v67
	ds_bpermute_b32 v67, v116, v66
	v_cvt_pk_bf16_f32 v70, v74, v75
	v_cvt_pk_bf16_f32 v71, v76, v77
	global_store_dwordx4 v[96:97], v[68:71], off offset:256
	s_and_saveexec_b64 s[2:3], s[40:41]
	s_cbranch_execz .LBB0_1928
	s_waitcnt lgkmcnt(0)
	v_add_f32_e32 v68, v66, v67
	s_lshl_b32 s16, s30, 2
	v_lshlrev_b64 v[66:67], 7, v[82:83]
	s_ashr_i32 s17, s16, 31
	v_lshl_add_u64 v[66:67], s[10:11], 0, v[66:67]
	v_lshl_add_u64 v[66:67], s[16:17], 2, v[66:67]
	v_readlane_b32 s16, v254, 53
	v_readlane_b32 s17, v254, 54
	s_mov_b32 s19, s17
	s_lshl_b32 s18, s37, 2
	v_writelane_b32 v254, s16, 53
	v_lshl_add_u64 v[66:67], v[66:67], 0, s[18:19]
	global_store_dword v[66:67], v68, off
	v_writelane_b32 v254, s17, 54
.LBB0_1928:
	s_or_b64 exec, exec, s[2:3]
	v_add_u32_e32 v66, 0x80, v158
	s_waitcnt lgkmcnt(0)
	v_ashrrev_i32_e32 v67, 31, v66
	v_lshlrev_b64 v[76:77], 13, v[66:67]
	v_lshl_add_u64 v[68:69], s[8:9], 0, v[76:77]
	v_lshl_add_u64 v[78:79], v[68:69], 0, v[156:157]
	s_nop 1
	v_readlane_b32 s2, v254, 57
	v_lshlrev_b64 v[80:81], 12, v[66:67]
	v_readlane_b32 s3, v254, 58
	v_lshl_add_u64 v[76:77], s[0:1], 0, v[76:77]
	v_lshl_add_u64 v[76:77], v[76:77], 0, v[156:157]
	v_lshl_add_u64 v[80:81], s[2:3], 0, v[80:81]
	v_lshl_add_u64 v[80:81], v[154:155], 1, v[80:81]
	s_waitcnt vmcnt(28)
	s_nop 1
	v_mov_b64_e32 v[68:69], v[192:193]
	v_mov_b64_e32 v[70:71], v[194:195]
	v_mov_b64_e32 v[72:73], v[196:197]
	v_mov_b64_e32 v[74:75], v[198:199]
	v_pk_add_f32 v[64:65], v[64:65], v[70:71]
	v_pk_add_f32 v[62:63], v[62:63], v[68:69]
	v_pk_add_f32 v[60:61], v[60:61], v[74:75]
	v_pk_add_f32 v[58:59], v[58:59], v[72:73]
	global_store_dwordx4 v[76:77], v[62:65], off
	global_store_dwordx4 v[76:77], v[58:61], off offset:16
	v_cvt_pk_bf16_f32 v68, v62, v63
	v_cvt_pk_bf16_f32 v69, v64, v65
	v_cvt_pk_bf16_f32 v70, v58, v59
	v_cvt_pk_bf16_f32 v71, v60, v61
	global_store_dwordx4 v[80:81], v[68:71], off
	s_nop 1
	v_mul_f32_e32 v63, v63, v63
	v_mul_f32_e32 v65, v65, v65
	v_mul_f32_e32 v59, v59, v59
	v_fmac_f32_e32 v63, v62, v62
	v_fmac_f32_e32 v65, v64, v64
	v_mul_f32_e32 v61, v61, v61
	v_fmac_f32_e32 v59, v58, v58
	v_add_f32_e32 v58, v63, v65
	v_fmac_f32_e32 v61, v60, v60
	v_add_f32_e32 v58, v58, v59
	v_add_f32_e32 v62, v61, v58
	s_waitcnt vmcnt(29)
	s_nop 1
	v_mov_b64_e32 v[68:69], v[200:201]
	v_mov_b64_e32 v[70:71], v[202:203]
	v_mov_b64_e32 v[72:73], v[204:205]
	v_mov_b64_e32 v[74:75], v[206:207]
	s_mov_b64 s[100:101], 0x160000
	v_lshl_add_u64 v[250:251], v[248:249], 0, s[100:101]
	global_load_dwordx4 v[192:195], v[250:251], off
	global_load_dwordx4 v[196:199], v[250:251], off offset:16
	global_load_dwordx4 v[200:203], v[250:251], off offset:512
	global_load_dwordx4 v[204:207], v[250:251], off offset:528
	v_pk_add_f32 v[56:57], v[56:57], v[70:71]
	v_pk_add_f32 v[54:55], v[54:55], v[68:69]
	v_pk_add_f32 v[58:59], v[50:51], v[72:73]
	v_mul_f32_e32 v50, v55, v55
	v_mul_f32_e32 v51, v57, v57
	v_pk_add_f32 v[60:61], v[52:53], v[74:75]
	v_mul_f32_e32 v52, v59, v59
	v_fmac_f32_e32 v50, v54, v54
	v_fmac_f32_e32 v51, v56, v56
	v_mul_f32_e32 v53, v61, v61
	v_fmac_f32_e32 v52, v58, v58
	v_add_f32_e32 v50, v50, v51
	v_add_f32_e32 v50, v50, v52
	v_fmac_f32_e32 v53, v60, v60
	v_add_f32_e32 v50, v53, v50
	v_add_f32_e32 v50, v62, v50
	ds_bpermute_b32 v51, v122, v50
	global_store_dwordx4 v[76:77], v[54:57], off offset:512
	global_store_dwordx4 v[76:77], v[58:61], off offset:528
	v_cvt_pk_bf16_f32 v52, v54, v55
	v_cvt_pk_bf16_f32 v53, v56, v57
	s_waitcnt lgkmcnt(0)
	v_add_f32_e32 v50, v50, v51
	ds_bpermute_b32 v51, v116, v50
	v_cvt_pk_bf16_f32 v54, v58, v59
	v_cvt_pk_bf16_f32 v55, v60, v61
	global_store_dwordx4 v[80:81], v[52:55], off offset:256
	s_and_saveexec_b64 s[2:3], s[40:41]
	s_cbranch_execz .LBB0_1930
; __device__ __forceinline__ unsigned cvt_pk_bf16(float lo, float hi) { unsigned r; asm volatile("v_cvt_pk_bf16_f32 %0, %1, %2" : "=v"(r) : "v"(lo), "v"(hi)); return r; }
;     __device__ __forceinline__ void operator()(f32x4 (&acc)[2][2][4][2], const Unit& u, int wr, int wc, int fr, int fq) const {
;         const int row0 = u.pm * BM + wr * 64 + fr; const int col0 = u.pn * BM + wc * 32 + 8 * fq;
; #pragma unroll
;         for (int ai = 0; ai < 2; ++ai)
; #pragma unroll
;             for (int m = 0; m < 4; ++m) { const int row = row0 + ai * HALF + m * 16; float* rowp = X + (size_t)row * ldc + col0; const float* rowi = Xi + (size_t)row * ldc + col0; bf16_t* rowb = XB + (size_t)row * ldc + col0;
;                 float sq = 0.f;
; #pragma unroll
;                 for (int bj = 0; bj < 2; ++bj) { f32x4* p = (f32x4*)(rowp + bj * HALF); const f32x4* pi = (const f32x4*)(rowi + bj * HALF); const f32x4 x0 = pi[0] + acc[ai][bj][m][0], x1 = pi[1] + acc[ai][bj][m][1];
;                     p[0] = x0; p[1] = x1;
;                     u32x4 w; w.x = cvt_pk_bf16(x0[0], x0[1]); w.y = cvt_pk_bf16(x0[2], x0[3]); w.z = cvt_pk_bf16(x1[0], x1[1]); w.w = cvt_pk_bf16(x1[2], x1[3]);
;                     *(u32x4*)(rowb + bj * HALF) = w;
;                     sq += (x0[0] * x0[0] + x0[1] * x0[1]) + (x0[2] * x0[2] + x0[3] * x0[3]) + (x1[0] * x1[0] + x1[1] * x1[1]) + (x1[2] * x1[2] + x1[3] * x1[3]); }
;                 sq += __shfl_xor(sq, 16); sq += __shfl_xor(sq, 32);
;                 if (fq == 0) ss[(size_t)row * 32 + u.pn * 4 + wc] = sq; }
;     }
	s_waitcnt lgkmcnt(0)
	v_add_f32_e32 v52, v50, v51
	s_lshl_b32 s16, s30, 2
	v_lshlrev_b64 v[50:51], 7, v[66:67]
	s_ashr_i32 s17, s16, 31
	v_lshl_add_u64 v[50:51], s[10:11], 0, v[50:51]
	v_lshl_add_u64 v[50:51], s[16:17], 2, v[50:51]
	v_readlane_b32 s16, v254, 53
	v_readlane_b32 s17, v254, 54
	s_mov_b32 s19, s17
	s_lshl_b32 s18, s37, 2
	v_writelane_b32 v254, s16, 53
	v_lshl_add_u64 v[50:51], v[50:51], 0, s[18:19]
	global_store_dword v[50:51], v52, off
	v_writelane_b32 v254, s17, 54
.LBB0_1930:
	s_or_b64 exec, exec, s[2:3]
	v_add_u32_e32 v50, 0x90, v158
	s_waitcnt lgkmcnt(0)
	v_ashrrev_i32_e32 v51, 31, v50
	v_lshlrev_b64 v[60:61], 13, v[50:51]
	v_lshl_add_u64 v[52:53], s[8:9], 0, v[60:61]
	v_lshl_add_u64 v[62:63], v[52:53], 0, v[156:157]
	s_nop 1
	v_readlane_b32 s2, v254, 57
	v_lshlrev_b64 v[64:65], 12, v[50:51]
	v_readlane_b32 s3, v254, 58
	v_lshl_add_u64 v[60:61], s[0:1], 0, v[60:61]
	v_lshl_add_u64 v[60:61], v[60:61], 0, v[156:157]
	v_lshl_add_u64 v[64:65], s[2:3], 0, v[64:65]
	v_lshl_add_u64 v[64:65], v[154:155], 1, v[64:65]
	s_waitcnt vmcnt(28)
	s_nop 1
	v_mov_b64_e32 v[52:53], v[232:233]
	v_mov_b64_e32 v[54:55], v[234:235]
	v_mov_b64_e32 v[56:57], v[236:237]
	v_mov_b64_e32 v[58:59], v[238:239]
	v_pk_add_f32 v[48:49], v[48:49], v[54:55]
	v_pk_add_f32 v[46:47], v[46:47], v[52:53]
	v_pk_add_f32 v[44:45], v[44:45], v[58:59]
	v_pk_add_f32 v[42:43], v[42:43], v[56:57]
	global_store_dwordx4 v[60:61], v[46:49], off
	global_store_dwordx4 v[60:61], v[42:45], off offset:16
	v_cvt_pk_bf16_f32 v52, v46, v47
	v_cvt_pk_bf16_f32 v53, v48, v49
	v_cvt_pk_bf16_f32 v54, v42, v43
	v_cvt_pk_bf16_f32 v55, v44, v45
	global_store_dwordx4 v[64:65], v[52:55], off
	s_nop 1
	v_mul_f32_e32 v47, v47, v47
	v_mul_f32_e32 v49, v49, v49
	v_mul_f32_e32 v43, v43, v43
	v_fmac_f32_e32 v47, v46, v46
	v_fmac_f32_e32 v49, v48, v48
	v_mul_f32_e32 v45, v45, v45
	v_fmac_f32_e32 v43, v42, v42
	v_add_f32_e32 v42, v47, v49
	v_fmac_f32_e32 v45, v44, v44
	v_add_f32_e32 v42, v42, v43
	v_add_f32_e32 v46, v45, v42
	s_waitcnt vmcnt(29)
	s_nop 1
	v_mov_b64_e32 v[52:53], v[240:241]
	v_mov_b64_e32 v[54:55], v[242:243]
	v_mov_b64_e32 v[56:57], v[244:245]
	v_mov_b64_e32 v[58:59], v[246:247]
	v_pk_add_f32 v[40:41], v[40:41], v[54:55]
	v_pk_add_f32 v[38:39], v[38:39], v[52:53]
	v_pk_add_f32 v[42:43], v[34:35], v[56:57]
	v_mul_f32_e32 v34, v39, v39
	v_mul_f32_e32 v35, v41, v41
	v_pk_add_f32 v[44:45], v[36:37], v[58:59]
	v_mul_f32_e32 v36, v43, v43
	v_fmac_f32_e32 v34, v38, v38
	v_fmac_f32_e32 v35, v40, v40
	v_mul_f32_e32 v37, v45, v45
	v_fmac_f32_e32 v36, v42, v42
	v_add_f32_e32 v34, v34, v35
	v_add_f32_e32 v34, v34, v36
	v_fmac_f32_e32 v37, v44, v44
	v_add_f32_e32 v34, v37, v34
	v_add_f32_e32 v34, v46, v34
	ds_bpermute_b32 v35, v122, v34
	global_store_dwordx4 v[60:61], v[38:41], off offset:512
	global_store_dwordx4 v[60:61], v[42:45], off offset:528
	v_cvt_pk_bf16_f32 v36, v38, v39
	v_cvt_pk_bf16_f32 v37, v40, v41
	s_waitcnt lgkmcnt(0)
	v_add_f32_e32 v34, v34, v35
	ds_bpermute_b32 v35, v116, v34
	v_cvt_pk_bf16_f32 v38, v42, v43
	v_cvt_pk_bf16_f32 v39, v44, v45
	global_store_dwordx4 v[64:65], v[36:39], off offset:256
	s_and_saveexec_b64 s[2:3], s[40:41]
	s_cbranch_execz .LBB0_1932
	s_waitcnt lgkmcnt(0)
	v_add_f32_e32 v36, v34, v35
	s_lshl_b32 s16, s30, 2
	v_lshlrev_b64 v[34:35], 7, v[50:51]
	s_ashr_i32 s17, s16, 31
	v_lshl_add_u64 v[34:35], s[10:11], 0, v[34:35]
	v_lshl_add_u64 v[34:35], s[16:17], 2, v[34:35]
	v_readlane_b32 s16, v254, 53
	v_readlane_b32 s17, v254, 54
	s_mov_b32 s19, s17
	s_lshl_b32 s18, s37, 2
	v_writelane_b32 v254, s16, 53
	v_lshl_add_u64 v[34:35], v[34:35], 0, s[18:19]
	global_store_dword v[34:35], v36, off
	v_writelane_b32 v254, s17, 54
; __device__ __forceinline__ unsigned cvt_pk_bf16(float lo, float hi) { unsigned r; asm volatile("v_cvt_pk_bf16_f32 %0, %1, %2" : "=v"(r) : "v"(lo), "v"(hi)); return r; }
;     __device__ __forceinline__ void operator()(f32x4 (&acc)[2][2][4][2], const Unit& u, int wr, int wc, int fr, int fq) const {
;         const int row0 = u.pm * BM + wr * 64 + fr; const int col0 = u.pn * BM + wc * 32 + 8 * fq;
; #pragma unroll
;         for (int ai = 0; ai < 2; ++ai)
; #pragma unroll
;             for (int m = 0; m < 4; ++m) { const int row = row0 + ai * HALF + m * 16; float* rowp = X + (size_t)row * ldc + col0; const float* rowi = Xi + (size_t)row * ldc + col0; bf16_t* rowb = XB + (size_t)row * ldc + col0;
;                 float sq = 0.f;
; #pragma unroll
;                 for (int bj = 0; bj < 2; ++bj) { f32x4* p = (f32x4*)(rowp + bj * HALF); const f32x4* pi = (const f32x4*)(rowi + bj * HALF); const f32x4 x0 = pi[0] + acc[ai][bj][m][0], x1 = pi[1] + acc[ai][bj][m][1];
;                     p[0] = x0; p[1] = x1;
;                     u32x4 w; w.x = cvt_pk_bf16(x0[0], x0[1]); w.y = cvt_pk_bf16(x0[2], x0[3]); w.z = cvt_pk_bf16(x1[0], x1[1]); w.w = cvt_pk_bf16(x1[2], x1[3]);
;                     *(u32x4*)(rowb + bj * HALF) = w;
;                     sq += (x0[0] * x0[0] + x0[1] * x0[1]) + (x0[2] * x0[2] + x0[3] * x0[3]) + (x1[0] * x1[0] + x1[1] * x1[1]) + (x1[2] * x1[2] + x1[3] * x1[3]); }
;                 sq += __shfl_xor(sq, 16); sq += __shfl_xor(sq, 32);
;                 if (fq == 0) ss[(size_t)row * 32 + u.pn * 4 + wc] = sq; }
;     }
.LBB0_1932:
	s_or_b64 exec, exec, s[2:3]
	v_add_u32_e32 v34, 0xa0, v158
	s_waitcnt lgkmcnt(0)
	v_ashrrev_i32_e32 v35, 31, v34
	v_lshlrev_b64 v[44:45], 13, v[34:35]
	v_lshl_add_u64 v[36:37], s[8:9], 0, v[44:45]
	v_lshl_add_u64 v[46:47], v[36:37], 0, v[156:157]
	s_nop 1
	v_readlane_b32 s2, v254, 57
	v_lshlrev_b64 v[48:49], 12, v[34:35]
	v_readlane_b32 s3, v254, 58
	v_lshl_add_u64 v[44:45], s[0:1], 0, v[44:45]
	v_lshl_add_u64 v[44:45], v[44:45], 0, v[156:157]
	v_lshl_add_u64 v[48:49], s[2:3], 0, v[48:49]
	v_lshl_add_u64 v[48:49], v[154:155], 1, v[48:49]
	s_waitcnt vmcnt(24)
	s_nop 1
	v_mov_b64_e32 v[36:37], v[176:177]
	v_mov_b64_e32 v[38:39], v[178:179]
	v_mov_b64_e32 v[40:41], v[180:181]
	v_mov_b64_e32 v[42:43], v[182:183]
	v_pk_add_f32 v[32:33], v[32:33], v[38:39]
	v_pk_add_f32 v[30:31], v[30:31], v[36:37]
	v_pk_add_f32 v[28:29], v[28:29], v[42:43]
	v_pk_add_f32 v[26:27], v[26:27], v[40:41]
	global_store_dwordx4 v[44:45], v[30:33], off
	global_store_dwordx4 v[44:45], v[26:29], off offset:16
	v_cvt_pk_bf16_f32 v36, v30, v31
	v_cvt_pk_bf16_f32 v37, v32, v33
	v_cvt_pk_bf16_f32 v38, v26, v27
	v_cvt_pk_bf16_f32 v39, v28, v29
	global_store_dwordx4 v[48:49], v[36:39], off
	s_nop 1
	v_mul_f32_e32 v31, v31, v31
	v_mul_f32_e32 v33, v33, v33
	v_mul_f32_e32 v27, v27, v27
	v_fmac_f32_e32 v31, v30, v30
	v_fmac_f32_e32 v33, v32, v32
	v_mul_f32_e32 v29, v29, v29
	v_fmac_f32_e32 v27, v26, v26
	v_add_f32_e32 v26, v31, v33
	v_fmac_f32_e32 v29, v28, v28
	v_add_f32_e32 v26, v26, v27
	v_add_f32_e32 v30, v29, v26
	s_waitcnt vmcnt(25)
	s_nop 1
	v_mov_b64_e32 v[36:37], v[184:185]
	v_mov_b64_e32 v[38:39], v[186:187]
	v_mov_b64_e32 v[40:41], v[188:189]
	v_mov_b64_e32 v[42:43], v[190:191]
	v_pk_add_f32 v[24:25], v[24:25], v[38:39]
	v_pk_add_f32 v[22:23], v[22:23], v[36:37]
	v_pk_add_f32 v[26:27], v[18:19], v[40:41]
	v_mul_f32_e32 v18, v23, v23
	v_mul_f32_e32 v19, v25, v25
	v_pk_add_f32 v[28:29], v[20:21], v[42:43]
	v_mul_f32_e32 v20, v27, v27
	v_fmac_f32_e32 v18, v22, v22
	v_fmac_f32_e32 v19, v24, v24
	v_mul_f32_e32 v21, v29, v29
	v_fmac_f32_e32 v20, v26, v26
	v_add_f32_e32 v18, v18, v19
	v_add_f32_e32 v18, v18, v20
	v_fmac_f32_e32 v21, v28, v28
	v_add_f32_e32 v18, v21, v18
	v_add_f32_e32 v18, v30, v18
	ds_bpermute_b32 v19, v122, v18
	global_store_dwordx4 v[44:45], v[22:25], off offset:512
	global_store_dwordx4 v[44:45], v[26:29], off offset:528
	v_cvt_pk_bf16_f32 v20, v22, v23
	v_cvt_pk_bf16_f32 v21, v24, v25
	s_waitcnt lgkmcnt(0)
	v_add_f32_e32 v18, v18, v19
	ds_bpermute_b32 v19, v116, v18
	v_cvt_pk_bf16_f32 v22, v26, v27
	v_cvt_pk_bf16_f32 v23, v28, v29
	global_store_dwordx4 v[48:49], v[20:23], off offset:256
	s_and_saveexec_b64 s[2:3], s[40:41]
	s_cbranch_execz .LBB0_1934
	s_waitcnt lgkmcnt(0)
	v_add_f32_e32 v20, v18, v19
	s_lshl_b32 s16, s30, 2
	v_lshlrev_b64 v[18:19], 7, v[34:35]
	s_ashr_i32 s17, s16, 31
	v_lshl_add_u64 v[18:19], s[10:11], 0, v[18:19]
	v_lshl_add_u64 v[18:19], s[16:17], 2, v[18:19]
	v_readlane_b32 s16, v254, 53
	v_readlane_b32 s17, v254, 54
	s_mov_b32 s19, s17
	s_lshl_b32 s18, s37, 2
	v_writelane_b32 v254, s16, 53
	v_lshl_add_u64 v[18:19], v[18:19], 0, s[18:19]
	global_store_dword v[18:19], v20, off
	v_writelane_b32 v254, s17, 54
.LBB0_1934:
	s_or_b64 exec, exec, s[2:3]
	v_add_u32_e32 v18, 0xb0, v158
	s_waitcnt lgkmcnt(0)
	v_ashrrev_i32_e32 v19, 31, v18
	v_lshlrev_b64 v[20:21], 13, v[18:19]
	v_lshl_add_u64 v[22:23], s[0:1], 0, v[20:21]
	v_lshl_add_u64 v[20:21], s[8:9], 0, v[20:21]
	v_readlane_b32 s2, v254, 57
	v_lshl_add_u64 v[30:31], v[20:21], 0, v[156:157]
	v_lshlrev_b64 v[20:21], 12, v[18:19]
	v_readlane_b32 s3, v254, 58
	v_lshl_add_u64 v[28:29], v[22:23], 0, v[156:157]
	s_nop 0
	v_lshl_add_u64 v[20:21], s[2:3], 0, v[20:21]
	v_lshl_add_u64 v[32:33], v[154:155], 1, v[20:21]
	s_nop 1
	s_waitcnt vmcnt(20)
	s_nop 1
	v_mov_b64_e32 v[24:25], v[192:193]
	v_mov_b64_e32 v[26:27], v[194:195]
	v_mov_b64_e32 v[20:21], v[196:197]
	v_mov_b64_e32 v[22:23], v[198:199]
	v_pk_add_f32 v[12:13], v[12:13], v[22:23]
	v_pk_add_f32 v[16:17], v[16:17], v[26:27]
	v_pk_add_f32 v[14:15], v[14:15], v[24:25]
	v_pk_add_f32 v[10:11], v[10:11], v[20:21]
	global_store_dwordx4 v[28:29], v[14:17], off
	global_store_dwordx4 v[28:29], v[10:13], off offset:16
	v_cvt_pk_bf16_f32 v20, v14, v15
	v_cvt_pk_bf16_f32 v21, v16, v17
	v_cvt_pk_bf16_f32 v22, v10, v11
	v_cvt_pk_bf16_f32 v23, v12, v13
	s_nop 0
	v_mul_f32_e32 v15, v15, v15
	v_fmac_f32_e32 v15, v14, v14
	v_mul_f32_e32 v14, v17, v17
	v_fmac_f32_e32 v14, v16, v16
	v_mul_f32_e32 v11, v11, v11
	v_add_f32_e32 v14, v15, v14
	v_fmac_f32_e32 v11, v10, v10
	v_add_f32_e32 v10, v14, v11
	v_mul_f32_e32 v11, v13, v13
	global_store_dwordx4 v[32:33], v[20:23], off
	v_fmac_f32_e32 v11, v12, v12
	s_nop 0
	v_add_f32_e32 v20, v11, v10
	s_nop 1
	s_waitcnt vmcnt(21)
	s_nop 1
	v_mov_b64_e32 v[14:15], v[200:201]
	v_mov_b64_e32 v[16:17], v[202:203]
	v_mov_b64_e32 v[10:11], v[204:205]
	v_mov_b64_e32 v[12:13], v[206:207]
	v_pk_add_f32 v[4:5], v[4:5], v[12:13]
	v_pk_add_f32 v[8:9], v[8:9], v[16:17]
	v_pk_add_f32 v[6:7], v[6:7], v[14:15]
	v_pk_add_f32 v[2:3], v[2:3], v[10:11]
	global_store_dwordx4 v[28:29], v[6:9], off offset:512
	global_store_dwordx4 v[28:29], v[2:5], off offset:528
	v_cvt_pk_bf16_f32 v10, v6, v7
	v_cvt_pk_bf16_f32 v11, v8, v9
	v_cvt_pk_bf16_f32 v12, v2, v3
	v_cvt_pk_bf16_f32 v13, v4, v5
	s_nop 0
	v_mul_f32_e32 v7, v7, v7
	v_fmac_f32_e32 v7, v6, v6
	v_mul_f32_e32 v6, v9, v9
	v_fmac_f32_e32 v6, v8, v8
	v_mul_f32_e32 v3, v3, v3
	v_add_f32_e32 v6, v7, v6
	v_fmac_f32_e32 v3, v2, v2
	v_add_f32_e32 v2, v6, v3
	v_mul_f32_e32 v3, v5, v5
	v_fmac_f32_e32 v3, v4, v4
	v_add_f32_e32 v2, v3, v2
	v_add_f32_e32 v2, v20, v2
	ds_bpermute_b32 v3, v122, v2
	global_store_dwordx4 v[32:33], v[10:13], off offset:256
	s_waitcnt lgkmcnt(0)
	v_add_f32_e32 v2, v2, v3
	ds_bpermute_b32 v3, v116, v2
	s_and_saveexec_b64 s[2:3], s[40:41]
	s_cbranch_execz .LBB0_1936
	s_waitcnt lgkmcnt(0)
	v_add_f32_e32 v4, v2, v3
	s_lshl_b32 s16, s30, 2
	v_lshlrev_b64 v[2:3], 7, v[18:19]
	s_ashr_i32 s17, s16, 31
	v_lshl_add_u64 v[2:3], s[10:11], 0, v[2:3]
	v_lshl_add_u64 v[2:3], s[16:17], 2, v[2:3]
	v_readlane_b32 s16, v254, 53
	v_readlane_b32 s17, v254, 54
	s_mov_b32 s19, s17
	s_lshl_b32 s18, s37, 2
	v_writelane_b32 v254, s16, 53
	v_lshl_add_u64 v[2:3], v[2:3], 0, s[18:19]
	global_store_dword v[2:3], v4, off
	v_writelane_b32 v254, s17, 54
